# EpiResid: residual loads as full 128B lines as well (DPP row exchange after the load)
# speedup vs baseline: 1.0200x; 1.0027x over previous
; __device__ __forceinline__ unsigned cvt_pk_bf16(float lo, float hi) { unsigned r; asm volatile("v_cvt_pk_bf16_f32 %0, %1, %2" : "=v"(r) : "v"(lo), "v"(hi)); return r; }
;     __device__ __forceinline__ void operator()(const f32x4 (&acc)[2][2][4][2], const Unit& u, int wr, int wc, int fr, int fq) const {
;         const int row0 = u.pm * BM + wr * 64 + fr, col0 = u.pn * BM + wc * 32 + 4 * fq;
;         f32x4 bs[2][4];
; #pragma unroll
;         for (int q = 0; q < 4; ++q) bs[0][q] = *(const f32x4*)(xin + (size_t)row0 * ldc + col0 + (q >> 1) * HALF + (q & 1) * 16);
; #pragma unroll
;         for (int gi = 0; gi < 8; ++gi) {
;             const int ai = gi >> 2, m = gi & 3;
;             const int row = row0 + ai * HALF + m * 16;
;             const size_t off = (size_t)row * ldc + col0;
;             if (gi + 1 < 8) {
;                 const size_t offn = (size_t)(row0 + ((gi + 1) >> 2) * HALF + ((gi + 1) & 3) * 16) * ldc + col0;
; #pragma unroll
;                 for (int q = 0; q < 4; ++q) bs[(gi + 1) & 1][q] = *(const f32x4*)(xin + offn + (q >> 1) * HALF + (q & 1) * 16);
;             }
;             float sq = 0.f;
; #pragma unroll
;             for (int q = 0; q < 4; ++q) {
;                 const int bj = q >> 1, n = q & 1;
;                 const f32x4 o = bs[gi & 1][q] + acc[ai][bj][m][n];
;                 *(f32x4*)(out + off + bj * HALF + n * 16) = o;
;                 if (ss) {
;                     u32x2 w; w.x = cvt_pk_bf16(o[0], o[1]); w.y = cvt_pk_bf16(o[2], o[3]);
;                     *(u32x2*)(xb + off + bj * HALF + n * 16) = w;
;                     sq += (o[0] * o[0] + o[1] * o[1]) + (o[2] * o[2] + o[3] * o[3]);
;                 }
;             }
;             if (ss) { sq += __shfl_xor(sq, 16); sq += __shfl_xor(sq, 32); if (fq == 0) ss[(size_t)row * 32 + u.pn * 4 + wc] = sq; }
.LBB0_345:
	s_andn2_b64 vcc, exec, s[26:27]
	s_cbranch_vccnz .Lres_noss
	v_lshl_add_u32 v246, s55, 8, v188
	v_lshl_or_b32 v247, s2, 8, v190
	v_lshlrev_b32_e32 v247, 2, v247
	v_lshl_add_u32 v160, v246, 13, v247
	v_add_u32_e32 v161, 0x20000, v160
	v_add_u32_e32 v162, 0x40000, v160
	v_add_u32_e32 v163, 0x60000, v160
	v_add_u32_e32 v164, 0x100000, v160
	v_add_u32_e32 v165, 0x120000, v160
	v_add_u32_e32 v192, 0x140000, v160
	v_add_u32_e32 v193, 0x160000, v160
	s_lshl_b32 s34, s2, 4
	s_lshl_b32 s35, s46, 2
	s_add_i32 s34, s34, s35
	v_lshl_add_u32 v189, v246, 7, s34
	v_and_b32_e32 v246, 8, v188
	v_mov_b32_e32 v247, 0x10040
	v_cmp_eq_u32_e32 vcc, 0, v246
	v_mov_b32_e32 v246, 0xffff0040
	s_nop 0
	v_cndmask_b32_e32 v234, v246, v169, vcc
	v_cndmask_b32_e32 v235, 0, v247, vcc
	v_add_u32_e32 v236, v160, v234
	v_add_u32_e32 v237, v160, v235
	global_load_dwordx4 v[128:131], v236, s[14:15]
	global_load_dwordx4 v[132:135], v237, s[14:15]
	global_load_dwordx4 v[136:139], v236, s[14:15] offset:512
	global_load_dwordx4 v[140:143], v237, s[14:15] offset:512
	v_add_u32_e32 v236, v161, v234
	v_add_u32_e32 v237, v161, v235
	global_load_dwordx4 v[144:147], v236, s[14:15]
	global_load_dwordx4 v[148:151], v237, s[14:15]
	global_load_dwordx4 v[152:155], v236, s[14:15] offset:512
	global_load_dwordx4 v[156:159], v237, s[14:15] offset:512
	v_add_u32_e32 v236, v162, v234
	v_add_u32_e32 v237, v162, v235
	global_load_dwordx4 v[206:209], v236, s[14:15]
	global_load_dwordx4 v[210:213], v237, s[14:15]
	global_load_dwordx4 v[214:217], v236, s[14:15] offset:512
	global_load_dwordx4 v[218:221], v237, s[14:15] offset:512
	v_and_b32_e32 v245, 4, v190
	v_mul_u32_u24_e32 v245, 6, v245
	s_waitcnt vmcnt(8)
	v_mov_b32_dpp v222, v128 row_ror:8 row_mask:0xf bank_mask:0xf
	v_mov_b32_dpp v223, v129 row_ror:8 row_mask:0xf bank_mask:0xf
	v_mov_b32_dpp v224, v130 row_ror:8 row_mask:0xf bank_mask:0xf
	v_mov_b32_dpp v225, v131 row_ror:8 row_mask:0xf bank_mask:0xf
	v_mov_b32_dpp v226, v132 row_ror:8 row_mask:0xf bank_mask:0xf
	v_mov_b32_dpp v227, v133 row_ror:8 row_mask:0xf bank_mask:0xf
	v_mov_b32_dpp v228, v134 row_ror:8 row_mask:0xf bank_mask:0xf
	v_mov_b32_dpp v229, v135 row_ror:8 row_mask:0xf bank_mask:0xf
	v_cndmask_b32_e32 v230, v132, v128, vcc
	v_cndmask_b32_e32 v231, v133, v129, vcc
	v_cndmask_b32_e32 v232, v134, v130, vcc
	v_cndmask_b32_e32 v233, v135, v131, vcc
	v_cndmask_b32_e32 v222, v226, v222, vcc
	v_cndmask_b32_e32 v223, v227, v223, vcc
	v_cndmask_b32_e32 v224, v228, v224, vcc
	v_cndmask_b32_e32 v225, v229, v225, vcc
	v_pk_add_f32 v[124:125], v[230:231], v[124:125]
	v_pk_add_f32 v[126:127], v[232:233], v[126:127]
	v_pk_add_f32 v[120:121], v[222:223], v[120:121]
	v_pk_add_f32 v[122:123], v[224:225], v[122:123]
	v_mov_b32_dpp v222, v136 row_ror:8 row_mask:0xf bank_mask:0xf
	v_mov_b32_dpp v223, v137 row_ror:8 row_mask:0xf bank_mask:0xf
	v_mov_b32_dpp v224, v138 row_ror:8 row_mask:0xf bank_mask:0xf
	v_mov_b32_dpp v225, v139 row_ror:8 row_mask:0xf bank_mask:0xf
	v_mov_b32_dpp v226, v140 row_ror:8 row_mask:0xf bank_mask:0xf
	v_mov_b32_dpp v227, v141 row_ror:8 row_mask:0xf bank_mask:0xf
	v_mov_b32_dpp v228, v142 row_ror:8 row_mask:0xf bank_mask:0xf
	v_mov_b32_dpp v229, v143 row_ror:8 row_mask:0xf bank_mask:0xf
	v_cndmask_b32_e32 v230, v140, v136, vcc
	v_cndmask_b32_e32 v231, v141, v137, vcc
	v_cndmask_b32_e32 v232, v142, v138, vcc
	v_cndmask_b32_e32 v233, v143, v139, vcc
	v_cndmask_b32_e32 v222, v226, v222, vcc
	v_cndmask_b32_e32 v223, v227, v223, vcc
	v_cndmask_b32_e32 v224, v228, v224, vcc
	v_cndmask_b32_e32 v225, v229, v225, vcc
	v_pk_add_f32 v[116:117], v[230:231], v[116:117]
	v_pk_add_f32 v[118:119], v[232:233], v[118:119]
	v_pk_add_f32 v[108:109], v[222:223], v[108:109]
	v_pk_add_f32 v[110:111], v[224:225], v[110:111]
	v_add_u32_e32 v236, v163, v234
	v_add_u32_e32 v237, v163, v235
	global_load_dwordx4 v[128:131], v236, s[14:15]
	global_load_dwordx4 v[132:135], v237, s[14:15]
	global_load_dwordx4 v[136:139], v236, s[14:15] offset:512
	global_load_dwordx4 v[140:143], v237, s[14:15] offset:512
	v_add_u32_e32 v236, v160, v234
	v_add_u32_e32 v237, v160, v235
	v_mov_b32_dpp v222, v120 row_ror:8 row_mask:0xf bank_mask:0xf
	v_mov_b32_dpp v223, v121 row_ror:8 row_mask:0xf bank_mask:0xf
	v_mov_b32_dpp v224, v122 row_ror:8 row_mask:0xf bank_mask:0xf
	v_mov_b32_dpp v225, v123 row_ror:8 row_mask:0xf bank_mask:0xf
	v_cndmask_b32_e32 v226, v222, v124, vcc
	v_cndmask_b32_e32 v227, v223, v125, vcc
	v_cndmask_b32_e32 v228, v224, v126, vcc
	v_cndmask_b32_e32 v229, v225, v127, vcc
	v_cndmask_b32_e32 v230, v124, v222, vcc
	v_cndmask_b32_e32 v231, v125, v223, vcc
	v_cndmask_b32_e32 v232, v126, v224, vcc
	v_cndmask_b32_e32 v233, v127, v225, vcc
	global_store_dwordx4 v236, v[226:229], s[72:73]
	global_store_dwordx4 v237, v[230:233], s[72:73]
	v_mov_b32_dpp v222, v108 row_ror:8 row_mask:0xf bank_mask:0xf
	v_mov_b32_dpp v223, v109 row_ror:8 row_mask:0xf bank_mask:0xf
	v_mov_b32_dpp v224, v110 row_ror:8 row_mask:0xf bank_mask:0xf
	v_mov_b32_dpp v225, v111 row_ror:8 row_mask:0xf bank_mask:0xf
	v_cndmask_b32_e32 v226, v222, v116, vcc
	v_cndmask_b32_e32 v227, v223, v117, vcc
	v_cndmask_b32_e32 v228, v224, v118, vcc
	v_cndmask_b32_e32 v229, v225, v119, vcc
	v_cndmask_b32_e32 v230, v116, v222, vcc
	v_cndmask_b32_e32 v231, v117, v223, vcc
	v_cndmask_b32_e32 v232, v118, v224, vcc
	v_cndmask_b32_e32 v233, v119, v225, vcc
	global_store_dwordx4 v236, v[226:229], s[72:73] offset:512
	global_store_dwordx4 v237, v[230:233], s[72:73] offset:512
	v_lshrrev_b32_e32 v236, 1, v160
	v_add_u32_e32 v236, v236, v245
	v_cvt_pk_bf16_f32 v194, v124, v125
	v_cvt_pk_bf16_f32 v195, v126, v127
	v_mul_f32_e32 v246, v125, v125
	v_mul_f32_e32 v247, v127, v127
	v_fmac_f32_e32 v246, v124, v124
	v_fmac_f32_e32 v247, v126, v126
	v_add_f32_e32 v180, v246, v247
	v_cvt_pk_bf16_f32 v196, v120, v121
	v_cvt_pk_bf16_f32 v197, v122, v123
	v_mul_f32_e32 v246, v121, v121
	v_mul_f32_e32 v247, v123, v123
	v_fmac_f32_e32 v246, v120, v120
	v_fmac_f32_e32 v247, v122, v122
	v_add_f32_e32 v246, v246, v247
	v_add_f32_e32 v180, v246, v180
	v_permlane16_swap_b32_e32 v194, v196
	v_permlane16_swap_b32_e32 v195, v197
	global_store_dwordx4 v236, v[194:197], s[22:23]
	s_nop 1
	v_cvt_pk_bf16_f32 v194, v116, v117
	v_cvt_pk_bf16_f32 v195, v118, v119
	v_mul_f32_e32 v246, v117, v117
	v_mul_f32_e32 v247, v119, v119
	v_fmac_f32_e32 v246, v116, v116
	v_fmac_f32_e32 v247, v118, v118
	v_add_f32_e32 v246, v246, v247
	v_add_f32_e32 v180, v246, v180
	v_cvt_pk_bf16_f32 v196, v108, v109
	v_cvt_pk_bf16_f32 v197, v110, v111
	v_mul_f32_e32 v246, v109, v109
	v_mul_f32_e32 v247, v111, v111
	v_fmac_f32_e32 v246, v108, v108
	v_fmac_f32_e32 v247, v110, v110
	v_add_f32_e32 v246, v246, v247
	v_add_f32_e32 v180, v246, v180
	v_permlane16_swap_b32_e32 v194, v196
	v_permlane16_swap_b32_e32 v195, v197
	global_store_dwordx4 v236, v[194:197], s[22:23] offset:256
	s_nop 1
	s_waitcnt vmcnt(14)
; __device__ __forceinline__ unsigned cvt_pk_bf16(float lo, float hi) { unsigned r; asm volatile("v_cvt_pk_bf16_f32 %0, %1, %2" : "=v"(r) : "v"(lo), "v"(hi)); return r; }
;     __device__ __forceinline__ void operator()(const f32x4 (&acc)[2][2][4][2], const Unit& u, int wr, int wc, int fr, int fq) const {
;     ...
;         for (int gi = 0; gi < 8; ++gi) {
;             const int ai = gi >> 2, m = gi & 3;
;             const int row = row0 + ai * HALF + m * 16;
;             const size_t off = (size_t)row * ldc + col0;
;             if (gi + 1 < 8) {
;                 const size_t offn = (size_t)(row0 + ((gi + 1) >> 2) * HALF + ((gi + 1) & 3) * 16) * ldc + col0;
; #pragma unroll
;                 for (int q = 0; q < 4; ++q) bs[(gi + 1) & 1][q] = *(const f32x4*)(xin + offn + (q >> 1) * HALF + (q & 1) * 16);
;             }
;             float sq = 0.f;
; #pragma unroll
;             for (int q = 0; q < 4; ++q) {
;                 const int bj = q >> 1, n = q & 1;
;                 const f32x4 o = bs[gi & 1][q] + acc[ai][bj][m][n];
;                 *(f32x4*)(out + off + bj * HALF + n * 16) = o;
;                 if (ss) {
;                     u32x2 w; w.x = cvt_pk_bf16(o[0], o[1]); w.y = cvt_pk_bf16(o[2], o[3]);
;                     *(u32x2*)(xb + off + bj * HALF + n * 16) = w;
;                     sq += (o[0] * o[0] + o[1] * o[1]) + (o[2] * o[2] + o[3] * o[3]);
;                 }
;             }
;             if (ss) { sq += __shfl_xor(sq, 16); sq += __shfl_xor(sq, 32); if (fq == 0) ss[(size_t)row * 32 + u.pn * 4 + wc] = sq; }
	v_mov_b32_dpp v222, v144 row_ror:8 row_mask:0xf bank_mask:0xf
	v_mov_b32_dpp v223, v145 row_ror:8 row_mask:0xf bank_mask:0xf
	v_mov_b32_dpp v224, v146 row_ror:8 row_mask:0xf bank_mask:0xf
	v_mov_b32_dpp v225, v147 row_ror:8 row_mask:0xf bank_mask:0xf
	v_mov_b32_dpp v226, v148 row_ror:8 row_mask:0xf bank_mask:0xf
	v_mov_b32_dpp v227, v149 row_ror:8 row_mask:0xf bank_mask:0xf
	v_mov_b32_dpp v228, v150 row_ror:8 row_mask:0xf bank_mask:0xf
	v_mov_b32_dpp v229, v151 row_ror:8 row_mask:0xf bank_mask:0xf
	v_cndmask_b32_e32 v230, v148, v144, vcc
	v_cndmask_b32_e32 v231, v149, v145, vcc
	v_cndmask_b32_e32 v232, v150, v146, vcc
	v_cndmask_b32_e32 v233, v151, v147, vcc
	v_cndmask_b32_e32 v222, v226, v222, vcc
	v_cndmask_b32_e32 v223, v227, v223, vcc
	v_cndmask_b32_e32 v224, v228, v224, vcc
	v_cndmask_b32_e32 v225, v229, v225, vcc
	v_pk_add_f32 v[112:113], v[230:231], v[112:113]
	v_pk_add_f32 v[114:115], v[232:233], v[114:115]
	v_pk_add_f32 v[104:105], v[222:223], v[104:105]
	v_pk_add_f32 v[106:107], v[224:225], v[106:107]
	v_mov_b32_dpp v222, v152 row_ror:8 row_mask:0xf bank_mask:0xf
	v_mov_b32_dpp v223, v153 row_ror:8 row_mask:0xf bank_mask:0xf
	v_mov_b32_dpp v224, v154 row_ror:8 row_mask:0xf bank_mask:0xf
	v_mov_b32_dpp v225, v155 row_ror:8 row_mask:0xf bank_mask:0xf
	v_mov_b32_dpp v226, v156 row_ror:8 row_mask:0xf bank_mask:0xf
	v_mov_b32_dpp v227, v157 row_ror:8 row_mask:0xf bank_mask:0xf
	v_mov_b32_dpp v228, v158 row_ror:8 row_mask:0xf bank_mask:0xf
	v_mov_b32_dpp v229, v159 row_ror:8 row_mask:0xf bank_mask:0xf
	v_cndmask_b32_e32 v230, v156, v152, vcc
	v_cndmask_b32_e32 v231, v157, v153, vcc
	v_cndmask_b32_e32 v232, v158, v154, vcc
	v_cndmask_b32_e32 v233, v159, v155, vcc
	v_cndmask_b32_e32 v222, v226, v222, vcc
	v_cndmask_b32_e32 v223, v227, v223, vcc
	v_cndmask_b32_e32 v224, v228, v224, vcc
	v_cndmask_b32_e32 v225, v229, v225, vcc
	v_pk_add_f32 v[100:101], v[230:231], v[100:101]
	v_pk_add_f32 v[102:103], v[232:233], v[102:103]
	v_pk_add_f32 v[92:93], v[222:223], v[92:93]
	v_pk_add_f32 v[94:95], v[224:225], v[94:95]
	v_add_u32_e32 v236, v164, v234
	v_add_u32_e32 v237, v164, v235
	global_load_dwordx4 v[144:147], v236, s[14:15]
	global_load_dwordx4 v[148:151], v237, s[14:15]
	global_load_dwordx4 v[152:155], v236, s[14:15] offset:512
	global_load_dwordx4 v[156:159], v237, s[14:15] offset:512
	v_add_u32_e32 v236, v161, v234
	v_add_u32_e32 v237, v161, v235
	v_mov_b32_dpp v222, v104 row_ror:8 row_mask:0xf bank_mask:0xf
	v_mov_b32_dpp v223, v105 row_ror:8 row_mask:0xf bank_mask:0xf
	v_mov_b32_dpp v224, v106 row_ror:8 row_mask:0xf bank_mask:0xf
	v_mov_b32_dpp v225, v107 row_ror:8 row_mask:0xf bank_mask:0xf
	v_cndmask_b32_e32 v226, v222, v112, vcc
	v_cndmask_b32_e32 v227, v223, v113, vcc
	v_cndmask_b32_e32 v228, v224, v114, vcc
	v_cndmask_b32_e32 v229, v225, v115, vcc
	v_cndmask_b32_e32 v230, v112, v222, vcc
	v_cndmask_b32_e32 v231, v113, v223, vcc
	v_cndmask_b32_e32 v232, v114, v224, vcc
	v_cndmask_b32_e32 v233, v115, v225, vcc
	global_store_dwordx4 v236, v[226:229], s[72:73]
	global_store_dwordx4 v237, v[230:233], s[72:73]
	v_mov_b32_dpp v222, v92 row_ror:8 row_mask:0xf bank_mask:0xf
	v_mov_b32_dpp v223, v93 row_ror:8 row_mask:0xf bank_mask:0xf
	v_mov_b32_dpp v224, v94 row_ror:8 row_mask:0xf bank_mask:0xf
	v_mov_b32_dpp v225, v95 row_ror:8 row_mask:0xf bank_mask:0xf
	v_cndmask_b32_e32 v226, v222, v100, vcc
	v_cndmask_b32_e32 v227, v223, v101, vcc
	v_cndmask_b32_e32 v228, v224, v102, vcc
	v_cndmask_b32_e32 v229, v225, v103, vcc
	v_cndmask_b32_e32 v230, v100, v222, vcc
	v_cndmask_b32_e32 v231, v101, v223, vcc
	v_cndmask_b32_e32 v232, v102, v224, vcc
	v_cndmask_b32_e32 v233, v103, v225, vcc
	global_store_dwordx4 v236, v[226:229], s[72:73] offset:512
	global_store_dwordx4 v237, v[230:233], s[72:73] offset:512
	v_lshrrev_b32_e32 v236, 1, v161
	v_add_u32_e32 v236, v236, v245
	v_cvt_pk_bf16_f32 v194, v112, v113
	v_cvt_pk_bf16_f32 v195, v114, v115
	v_mul_f32_e32 v246, v113, v113
	v_mul_f32_e32 v247, v115, v115
	v_fmac_f32_e32 v246, v112, v112
	v_fmac_f32_e32 v247, v114, v114
	v_add_f32_e32 v181, v246, v247
	v_cvt_pk_bf16_f32 v196, v104, v105
	v_cvt_pk_bf16_f32 v197, v106, v107
	v_mul_f32_e32 v246, v105, v105
	v_mul_f32_e32 v247, v107, v107
	v_fmac_f32_e32 v246, v104, v104
	v_fmac_f32_e32 v247, v106, v106
	v_add_f32_e32 v246, v246, v247
	v_add_f32_e32 v181, v246, v181
	v_permlane16_swap_b32_e32 v194, v196
	v_permlane16_swap_b32_e32 v195, v197
	global_store_dwordx4 v236, v[194:197], s[22:23]
	s_nop 1
	v_cvt_pk_bf16_f32 v194, v100, v101
	v_cvt_pk_bf16_f32 v195, v102, v103
	v_mul_f32_e32 v246, v101, v101
	v_mul_f32_e32 v247, v103, v103
	v_fmac_f32_e32 v246, v100, v100
	v_fmac_f32_e32 v247, v102, v102
	v_add_f32_e32 v246, v246, v247
	v_add_f32_e32 v181, v246, v181
	v_cvt_pk_bf16_f32 v196, v92, v93
	v_cvt_pk_bf16_f32 v197, v94, v95
	v_mul_f32_e32 v246, v93, v93
	v_mul_f32_e32 v247, v95, v95
	v_fmac_f32_e32 v246, v92, v92
	v_fmac_f32_e32 v247, v94, v94
	v_add_f32_e32 v246, v246, v247
	v_add_f32_e32 v181, v246, v181
	v_permlane16_swap_b32_e32 v194, v196
	v_permlane16_swap_b32_e32 v195, v197
	global_store_dwordx4 v236, v[194:197], s[22:23] offset:256
	s_nop 1
	s_waitcnt vmcnt(20)
; __device__ __forceinline__ unsigned cvt_pk_bf16(float lo, float hi) { unsigned r; asm volatile("v_cvt_pk_bf16_f32 %0, %1, %2" : "=v"(r) : "v"(lo), "v"(hi)); return r; }
;     __device__ __forceinline__ void operator()(const f32x4 (&acc)[2][2][4][2], const Unit& u, int wr, int wc, int fr, int fq) const {
;     ...
;         for (int gi = 0; gi < 8; ++gi) {
;             const int ai = gi >> 2, m = gi & 3;
;             const int row = row0 + ai * HALF + m * 16;
;             const size_t off = (size_t)row * ldc + col0;
;             if (gi + 1 < 8) {
;                 const size_t offn = (size_t)(row0 + ((gi + 1) >> 2) * HALF + ((gi + 1) & 3) * 16) * ldc + col0;
; #pragma unroll
;                 for (int q = 0; q < 4; ++q) bs[(gi + 1) & 1][q] = *(const f32x4*)(xin + offn + (q >> 1) * HALF + (q & 1) * 16);
;             }
;             float sq = 0.f;
; #pragma unroll
;             for (int q = 0; q < 4; ++q) {
;                 const int bj = q >> 1, n = q & 1;
;                 const f32x4 o = bs[gi & 1][q] + acc[ai][bj][m][n];
;                 *(f32x4*)(out + off + bj * HALF + n * 16) = o;
;                 if (ss) {
;                     u32x2 w; w.x = cvt_pk_bf16(o[0], o[1]); w.y = cvt_pk_bf16(o[2], o[3]);
;                     *(u32x2*)(xb + off + bj * HALF + n * 16) = w;
;                     sq += (o[0] * o[0] + o[1] * o[1]) + (o[2] * o[2] + o[3] * o[3]);
;                 }
;             }
	v_mov_b32_dpp v222, v206 row_ror:8 row_mask:0xf bank_mask:0xf
	v_mov_b32_dpp v223, v207 row_ror:8 row_mask:0xf bank_mask:0xf
	v_mov_b32_dpp v224, v208 row_ror:8 row_mask:0xf bank_mask:0xf
	v_mov_b32_dpp v225, v209 row_ror:8 row_mask:0xf bank_mask:0xf
	v_mov_b32_dpp v226, v210 row_ror:8 row_mask:0xf bank_mask:0xf
	v_mov_b32_dpp v227, v211 row_ror:8 row_mask:0xf bank_mask:0xf
	v_mov_b32_dpp v228, v212 row_ror:8 row_mask:0xf bank_mask:0xf
	v_mov_b32_dpp v229, v213 row_ror:8 row_mask:0xf bank_mask:0xf
	v_cndmask_b32_e32 v230, v210, v206, vcc
	v_cndmask_b32_e32 v231, v211, v207, vcc
	v_cndmask_b32_e32 v232, v212, v208, vcc
	v_cndmask_b32_e32 v233, v213, v209, vcc
	v_cndmask_b32_e32 v222, v226, v222, vcc
	v_cndmask_b32_e32 v223, v227, v223, vcc
	v_cndmask_b32_e32 v224, v228, v224, vcc
	v_cndmask_b32_e32 v225, v229, v225, vcc
	v_pk_add_f32 v[96:97], v[230:231], v[96:97]
	v_pk_add_f32 v[98:99], v[232:233], v[98:99]
	v_pk_add_f32 v[88:89], v[222:223], v[88:89]
	v_pk_add_f32 v[90:91], v[224:225], v[90:91]
	v_mov_b32_dpp v222, v214 row_ror:8 row_mask:0xf bank_mask:0xf
	v_mov_b32_dpp v223, v215 row_ror:8 row_mask:0xf bank_mask:0xf
	v_mov_b32_dpp v224, v216 row_ror:8 row_mask:0xf bank_mask:0xf
	v_mov_b32_dpp v225, v217 row_ror:8 row_mask:0xf bank_mask:0xf
	v_mov_b32_dpp v226, v218 row_ror:8 row_mask:0xf bank_mask:0xf
	v_mov_b32_dpp v227, v219 row_ror:8 row_mask:0xf bank_mask:0xf
	v_mov_b32_dpp v228, v220 row_ror:8 row_mask:0xf bank_mask:0xf
	v_mov_b32_dpp v229, v221 row_ror:8 row_mask:0xf bank_mask:0xf
	v_cndmask_b32_e32 v230, v218, v214, vcc
	v_cndmask_b32_e32 v231, v219, v215, vcc
	v_cndmask_b32_e32 v232, v220, v216, vcc
	v_cndmask_b32_e32 v233, v221, v217, vcc
	v_cndmask_b32_e32 v222, v226, v222, vcc
	v_cndmask_b32_e32 v223, v227, v223, vcc
	v_cndmask_b32_e32 v224, v228, v224, vcc
	v_cndmask_b32_e32 v225, v229, v225, vcc
	v_pk_add_f32 v[84:85], v[230:231], v[84:85]
	v_pk_add_f32 v[86:87], v[232:233], v[86:87]
	v_pk_add_f32 v[76:77], v[222:223], v[76:77]
	v_pk_add_f32 v[78:79], v[224:225], v[78:79]
	v_add_u32_e32 v236, v165, v234
	v_add_u32_e32 v237, v165, v235
	global_load_dwordx4 v[206:209], v236, s[14:15]
	global_load_dwordx4 v[210:213], v237, s[14:15]
	global_load_dwordx4 v[214:217], v236, s[14:15] offset:512
	global_load_dwordx4 v[218:221], v237, s[14:15] offset:512
	v_add_u32_e32 v236, v162, v234
	v_add_u32_e32 v237, v162, v235
	v_mov_b32_dpp v222, v88 row_ror:8 row_mask:0xf bank_mask:0xf
	v_mov_b32_dpp v223, v89 row_ror:8 row_mask:0xf bank_mask:0xf
	v_mov_b32_dpp v224, v90 row_ror:8 row_mask:0xf bank_mask:0xf
	v_mov_b32_dpp v225, v91 row_ror:8 row_mask:0xf bank_mask:0xf
	v_cndmask_b32_e32 v226, v222, v96, vcc
	v_cndmask_b32_e32 v227, v223, v97, vcc
	v_cndmask_b32_e32 v228, v224, v98, vcc
	v_cndmask_b32_e32 v229, v225, v99, vcc
	v_cndmask_b32_e32 v230, v96, v222, vcc
	v_cndmask_b32_e32 v231, v97, v223, vcc
	v_cndmask_b32_e32 v232, v98, v224, vcc
	v_cndmask_b32_e32 v233, v99, v225, vcc
	global_store_dwordx4 v236, v[226:229], s[72:73]
	global_store_dwordx4 v237, v[230:233], s[72:73]
	v_mov_b32_dpp v222, v76 row_ror:8 row_mask:0xf bank_mask:0xf
	v_mov_b32_dpp v223, v77 row_ror:8 row_mask:0xf bank_mask:0xf
	v_mov_b32_dpp v224, v78 row_ror:8 row_mask:0xf bank_mask:0xf
	v_mov_b32_dpp v225, v79 row_ror:8 row_mask:0xf bank_mask:0xf
	v_cndmask_b32_e32 v226, v222, v84, vcc
	v_cndmask_b32_e32 v227, v223, v85, vcc
	v_cndmask_b32_e32 v228, v224, v86, vcc
	v_cndmask_b32_e32 v229, v225, v87, vcc
	v_cndmask_b32_e32 v230, v84, v222, vcc
	v_cndmask_b32_e32 v231, v85, v223, vcc
	v_cndmask_b32_e32 v232, v86, v224, vcc
	v_cndmask_b32_e32 v233, v87, v225, vcc
	global_store_dwordx4 v236, v[226:229], s[72:73] offset:512
	global_store_dwordx4 v237, v[230:233], s[72:73] offset:512
	v_lshrrev_b32_e32 v236, 1, v162
	v_add_u32_e32 v236, v236, v245
	v_cvt_pk_bf16_f32 v194, v96, v97
	v_cvt_pk_bf16_f32 v195, v98, v99
	v_mul_f32_e32 v246, v97, v97
	v_mul_f32_e32 v247, v99, v99
	v_fmac_f32_e32 v246, v96, v96
	v_fmac_f32_e32 v247, v98, v98
	v_add_f32_e32 v182, v246, v247
	v_cvt_pk_bf16_f32 v196, v88, v89
	v_cvt_pk_bf16_f32 v197, v90, v91
	v_mul_f32_e32 v246, v89, v89
	v_mul_f32_e32 v247, v91, v91
	v_fmac_f32_e32 v246, v88, v88
	v_fmac_f32_e32 v247, v90, v90
	v_add_f32_e32 v246, v246, v247
	v_add_f32_e32 v182, v246, v182
	v_permlane16_swap_b32_e32 v194, v196
	v_permlane16_swap_b32_e32 v195, v197
	global_store_dwordx4 v236, v[194:197], s[22:23]
	s_nop 1
	v_cvt_pk_bf16_f32 v194, v84, v85
	v_cvt_pk_bf16_f32 v195, v86, v87
	v_mul_f32_e32 v246, v85, v85
	v_mul_f32_e32 v247, v87, v87
	v_fmac_f32_e32 v246, v84, v84
	v_fmac_f32_e32 v247, v86, v86
	v_add_f32_e32 v246, v246, v247
	v_add_f32_e32 v182, v246, v182
	v_cvt_pk_bf16_f32 v196, v76, v77
	v_cvt_pk_bf16_f32 v197, v78, v79
	v_mul_f32_e32 v246, v77, v77
	v_mul_f32_e32 v247, v79, v79
	v_fmac_f32_e32 v246, v76, v76
	v_fmac_f32_e32 v247, v78, v78
	v_add_f32_e32 v246, v246, v247
	v_add_f32_e32 v182, v246, v182
	v_permlane16_swap_b32_e32 v194, v196
	v_permlane16_swap_b32_e32 v195, v197
	global_store_dwordx4 v236, v[194:197], s[22:23] offset:256
	s_nop 1
	s_waitcnt vmcnt(26)
; __device__ __forceinline__ unsigned cvt_pk_bf16(float lo, float hi) { unsigned r; asm volatile("v_cvt_pk_bf16_f32 %0, %1, %2" : "=v"(r) : "v"(lo), "v"(hi)); return r; }
;     __device__ __forceinline__ void operator()(const f32x4 (&acc)[2][2][4][2], const Unit& u, int wr, int wc, int fr, int fq) const {
;     ...
;         for (int gi = 0; gi < 8; ++gi) {
;             const int ai = gi >> 2, m = gi & 3;
;             const int row = row0 + ai * HALF + m * 16;
;             const size_t off = (size_t)row * ldc + col0;
;             if (gi + 1 < 8) {
;                 const size_t offn = (size_t)(row0 + ((gi + 1) >> 2) * HALF + ((gi + 1) & 3) * 16) * ldc + col0;
; #pragma unroll
;                 for (int q = 0; q < 4; ++q) bs[(gi + 1) & 1][q] = *(const f32x4*)(xin + offn + (q >> 1) * HALF + (q & 1) * 16);
;             }
;             float sq = 0.f;
; #pragma unroll
;             for (int q = 0; q < 4; ++q) {
;                 const int bj = q >> 1, n = q & 1;
;                 const f32x4 o = bs[gi & 1][q] + acc[ai][bj][m][n];
;                 *(f32x4*)(out + off + bj * HALF + n * 16) = o;
;                 if (ss) {
;                     u32x2 w; w.x = cvt_pk_bf16(o[0], o[1]); w.y = cvt_pk_bf16(o[2], o[3]);
;                     *(u32x2*)(xb + off + bj * HALF + n * 16) = w;
;                     sq += (o[0] * o[0] + o[1] * o[1]) + (o[2] * o[2] + o[3] * o[3]);
;                 }
;             }
	v_mov_b32_dpp v222, v128 row_ror:8 row_mask:0xf bank_mask:0xf
	v_mov_b32_dpp v223, v129 row_ror:8 row_mask:0xf bank_mask:0xf
	v_mov_b32_dpp v224, v130 row_ror:8 row_mask:0xf bank_mask:0xf
	v_mov_b32_dpp v225, v131 row_ror:8 row_mask:0xf bank_mask:0xf
	v_mov_b32_dpp v226, v132 row_ror:8 row_mask:0xf bank_mask:0xf
	v_mov_b32_dpp v227, v133 row_ror:8 row_mask:0xf bank_mask:0xf
	v_mov_b32_dpp v228, v134 row_ror:8 row_mask:0xf bank_mask:0xf
	v_mov_b32_dpp v229, v135 row_ror:8 row_mask:0xf bank_mask:0xf
	v_cndmask_b32_e32 v230, v132, v128, vcc
	v_cndmask_b32_e32 v231, v133, v129, vcc
	v_cndmask_b32_e32 v232, v134, v130, vcc
	v_cndmask_b32_e32 v233, v135, v131, vcc
	v_cndmask_b32_e32 v222, v226, v222, vcc
	v_cndmask_b32_e32 v223, v227, v223, vcc
	v_cndmask_b32_e32 v224, v228, v224, vcc
	v_cndmask_b32_e32 v225, v229, v225, vcc
	v_pk_add_f32 v[80:81], v[230:231], v[80:81]
	v_pk_add_f32 v[82:83], v[232:233], v[82:83]
	v_pk_add_f32 v[72:73], v[222:223], v[72:73]
	v_pk_add_f32 v[74:75], v[224:225], v[74:75]
	v_mov_b32_dpp v222, v136 row_ror:8 row_mask:0xf bank_mask:0xf
	v_mov_b32_dpp v223, v137 row_ror:8 row_mask:0xf bank_mask:0xf
	v_mov_b32_dpp v224, v138 row_ror:8 row_mask:0xf bank_mask:0xf
	v_mov_b32_dpp v225, v139 row_ror:8 row_mask:0xf bank_mask:0xf
	v_mov_b32_dpp v226, v140 row_ror:8 row_mask:0xf bank_mask:0xf
	v_mov_b32_dpp v227, v141 row_ror:8 row_mask:0xf bank_mask:0xf
	v_mov_b32_dpp v228, v142 row_ror:8 row_mask:0xf bank_mask:0xf
	v_mov_b32_dpp v229, v143 row_ror:8 row_mask:0xf bank_mask:0xf
	v_cndmask_b32_e32 v230, v140, v136, vcc
	v_cndmask_b32_e32 v231, v141, v137, vcc
	v_cndmask_b32_e32 v232, v142, v138, vcc
	v_cndmask_b32_e32 v233, v143, v139, vcc
	v_cndmask_b32_e32 v222, v226, v222, vcc
	v_cndmask_b32_e32 v223, v227, v223, vcc
	v_cndmask_b32_e32 v224, v228, v224, vcc
	v_cndmask_b32_e32 v225, v229, v225, vcc
	v_pk_add_f32 v[68:69], v[230:231], v[68:69]
	v_pk_add_f32 v[70:71], v[232:233], v[70:71]
	v_pk_add_f32 v[64:65], v[222:223], v[64:65]
	v_pk_add_f32 v[66:67], v[224:225], v[66:67]
	v_add_u32_e32 v236, v192, v234
	v_add_u32_e32 v237, v192, v235
	global_load_dwordx4 v[128:131], v236, s[14:15]
	global_load_dwordx4 v[132:135], v237, s[14:15]
	global_load_dwordx4 v[136:139], v236, s[14:15] offset:512
	global_load_dwordx4 v[140:143], v237, s[14:15] offset:512
	v_add_u32_e32 v236, v163, v234
	v_add_u32_e32 v237, v163, v235
	v_mov_b32_dpp v222, v72 row_ror:8 row_mask:0xf bank_mask:0xf
	v_mov_b32_dpp v223, v73 row_ror:8 row_mask:0xf bank_mask:0xf
	v_mov_b32_dpp v224, v74 row_ror:8 row_mask:0xf bank_mask:0xf
	v_mov_b32_dpp v225, v75 row_ror:8 row_mask:0xf bank_mask:0xf
	v_cndmask_b32_e32 v226, v222, v80, vcc
	v_cndmask_b32_e32 v227, v223, v81, vcc
	v_cndmask_b32_e32 v228, v224, v82, vcc
	v_cndmask_b32_e32 v229, v225, v83, vcc
	v_cndmask_b32_e32 v230, v80, v222, vcc
	v_cndmask_b32_e32 v231, v81, v223, vcc
	v_cndmask_b32_e32 v232, v82, v224, vcc
	v_cndmask_b32_e32 v233, v83, v225, vcc
	global_store_dwordx4 v236, v[226:229], s[72:73]
	global_store_dwordx4 v237, v[230:233], s[72:73]
	v_mov_b32_dpp v222, v64 row_ror:8 row_mask:0xf bank_mask:0xf
	v_mov_b32_dpp v223, v65 row_ror:8 row_mask:0xf bank_mask:0xf
	v_mov_b32_dpp v224, v66 row_ror:8 row_mask:0xf bank_mask:0xf
	v_mov_b32_dpp v225, v67 row_ror:8 row_mask:0xf bank_mask:0xf
	v_cndmask_b32_e32 v226, v222, v68, vcc
	v_cndmask_b32_e32 v227, v223, v69, vcc
	v_cndmask_b32_e32 v228, v224, v70, vcc
	v_cndmask_b32_e32 v229, v225, v71, vcc
	v_cndmask_b32_e32 v230, v68, v222, vcc
	v_cndmask_b32_e32 v231, v69, v223, vcc
	v_cndmask_b32_e32 v232, v70, v224, vcc
	v_cndmask_b32_e32 v233, v71, v225, vcc
	global_store_dwordx4 v236, v[226:229], s[72:73] offset:512
	global_store_dwordx4 v237, v[230:233], s[72:73] offset:512
	v_lshrrev_b32_e32 v236, 1, v163
	v_add_u32_e32 v236, v236, v245
	v_cvt_pk_bf16_f32 v194, v80, v81
	v_cvt_pk_bf16_f32 v195, v82, v83
	v_mul_f32_e32 v246, v81, v81
	v_mul_f32_e32 v247, v83, v83
	v_fmac_f32_e32 v246, v80, v80
	v_fmac_f32_e32 v247, v82, v82
	v_add_f32_e32 v183, v246, v247
	v_cvt_pk_bf16_f32 v196, v72, v73
	v_cvt_pk_bf16_f32 v197, v74, v75
	v_mul_f32_e32 v246, v73, v73
	v_mul_f32_e32 v247, v75, v75
	v_fmac_f32_e32 v246, v72, v72
	v_fmac_f32_e32 v247, v74, v74
	v_add_f32_e32 v246, v246, v247
	v_add_f32_e32 v183, v246, v183
	v_permlane16_swap_b32_e32 v194, v196
	v_permlane16_swap_b32_e32 v195, v197
	global_store_dwordx4 v236, v[194:197], s[22:23]
	s_nop 1
	v_cvt_pk_bf16_f32 v194, v68, v69
	v_cvt_pk_bf16_f32 v195, v70, v71
	v_mul_f32_e32 v246, v69, v69
	v_mul_f32_e32 v247, v71, v71
	v_fmac_f32_e32 v246, v68, v68
	v_fmac_f32_e32 v247, v70, v70
	v_add_f32_e32 v246, v246, v247
	v_add_f32_e32 v183, v246, v183
	v_cvt_pk_bf16_f32 v196, v64, v65
	v_cvt_pk_bf16_f32 v197, v66, v67
	v_mul_f32_e32 v246, v65, v65
	v_mul_f32_e32 v247, v67, v67
	v_fmac_f32_e32 v246, v64, v64
	v_fmac_f32_e32 v247, v66, v66
	v_add_f32_e32 v246, v246, v247
	v_add_f32_e32 v183, v246, v183
	v_permlane16_swap_b32_e32 v194, v196
	v_permlane16_swap_b32_e32 v195, v197
	global_store_dwordx4 v236, v[194:197], s[22:23] offset:256
	s_nop 1
	s_waitcnt vmcnt(26)
; __device__ __forceinline__ unsigned cvt_pk_bf16(float lo, float hi) { unsigned r; asm volatile("v_cvt_pk_bf16_f32 %0, %1, %2" : "=v"(r) : "v"(lo), "v"(hi)); return r; }
;     __device__ __forceinline__ void operator()(const f32x4 (&acc)[2][2][4][2], const Unit& u, int wr, int wc, int fr, int fq) const {
;     ...
;         for (int gi = 0; gi < 8; ++gi) {
;             const int ai = gi >> 2, m = gi & 3;
;             const int row = row0 + ai * HALF + m * 16;
;             const size_t off = (size_t)row * ldc + col0;
;             if (gi + 1 < 8) {
;                 const size_t offn = (size_t)(row0 + ((gi + 1) >> 2) * HALF + ((gi + 1) & 3) * 16) * ldc + col0;
; #pragma unroll
;                 for (int q = 0; q < 4; ++q) bs[(gi + 1) & 1][q] = *(const f32x4*)(xin + offn + (q >> 1) * HALF + (q & 1) * 16);
;             }
;             float sq = 0.f;
; #pragma unroll
;             for (int q = 0; q < 4; ++q) {
;                 const int bj = q >> 1, n = q & 1;
;                 const f32x4 o = bs[gi & 1][q] + acc[ai][bj][m][n];
;                 *(f32x4*)(out + off + bj * HALF + n * 16) = o;
;                 if (ss) {
;                     u32x2 w; w.x = cvt_pk_bf16(o[0], o[1]); w.y = cvt_pk_bf16(o[2], o[3]);
;                     *(u32x2*)(xb + off + bj * HALF + n * 16) = w;
;                     sq += (o[0] * o[0] + o[1] * o[1]) + (o[2] * o[2] + o[3] * o[3]);
;                 }
;             }
	v_mov_b32_dpp v222, v144 row_ror:8 row_mask:0xf bank_mask:0xf
	v_mov_b32_dpp v223, v145 row_ror:8 row_mask:0xf bank_mask:0xf
	v_mov_b32_dpp v224, v146 row_ror:8 row_mask:0xf bank_mask:0xf
	v_mov_b32_dpp v225, v147 row_ror:8 row_mask:0xf bank_mask:0xf
	v_mov_b32_dpp v226, v148 row_ror:8 row_mask:0xf bank_mask:0xf
	v_mov_b32_dpp v227, v149 row_ror:8 row_mask:0xf bank_mask:0xf
	v_mov_b32_dpp v228, v150 row_ror:8 row_mask:0xf bank_mask:0xf
	v_mov_b32_dpp v229, v151 row_ror:8 row_mask:0xf bank_mask:0xf
	v_cndmask_b32_e32 v230, v148, v144, vcc
	v_cndmask_b32_e32 v231, v149, v145, vcc
	v_cndmask_b32_e32 v232, v150, v146, vcc
	v_cndmask_b32_e32 v233, v151, v147, vcc
	v_cndmask_b32_e32 v222, v226, v222, vcc
	v_cndmask_b32_e32 v223, v227, v223, vcc
	v_cndmask_b32_e32 v224, v228, v224, vcc
	v_cndmask_b32_e32 v225, v229, v225, vcc
	v_pk_add_f32 v[60:61], v[230:231], v[60:61]
	v_pk_add_f32 v[62:63], v[232:233], v[62:63]
	v_pk_add_f32 v[56:57], v[222:223], v[56:57]
	v_pk_add_f32 v[58:59], v[224:225], v[58:59]
	v_mov_b32_dpp v222, v152 row_ror:8 row_mask:0xf bank_mask:0xf
	v_mov_b32_dpp v223, v153 row_ror:8 row_mask:0xf bank_mask:0xf
	v_mov_b32_dpp v224, v154 row_ror:8 row_mask:0xf bank_mask:0xf
	v_mov_b32_dpp v225, v155 row_ror:8 row_mask:0xf bank_mask:0xf
	v_mov_b32_dpp v226, v156 row_ror:8 row_mask:0xf bank_mask:0xf
	v_mov_b32_dpp v227, v157 row_ror:8 row_mask:0xf bank_mask:0xf
	v_mov_b32_dpp v228, v158 row_ror:8 row_mask:0xf bank_mask:0xf
	v_mov_b32_dpp v229, v159 row_ror:8 row_mask:0xf bank_mask:0xf
	v_cndmask_b32_e32 v230, v156, v152, vcc
	v_cndmask_b32_e32 v231, v157, v153, vcc
	v_cndmask_b32_e32 v232, v158, v154, vcc
	v_cndmask_b32_e32 v233, v159, v155, vcc
	v_cndmask_b32_e32 v222, v226, v222, vcc
	v_cndmask_b32_e32 v223, v227, v223, vcc
	v_cndmask_b32_e32 v224, v228, v224, vcc
	v_cndmask_b32_e32 v225, v229, v225, vcc
	v_pk_add_f32 v[52:53], v[230:231], v[52:53]
	v_pk_add_f32 v[54:55], v[232:233], v[54:55]
	v_pk_add_f32 v[44:45], v[222:223], v[44:45]
	v_pk_add_f32 v[46:47], v[224:225], v[46:47]
	v_add_u32_e32 v236, v193, v234
	v_add_u32_e32 v237, v193, v235
	global_load_dwordx4 v[144:147], v236, s[14:15]
	global_load_dwordx4 v[148:151], v237, s[14:15]
	global_load_dwordx4 v[152:155], v236, s[14:15] offset:512
	global_load_dwordx4 v[156:159], v237, s[14:15] offset:512
	v_add_u32_e32 v236, v164, v234
	v_add_u32_e32 v237, v164, v235
	v_mov_b32_dpp v222, v56 row_ror:8 row_mask:0xf bank_mask:0xf
	v_mov_b32_dpp v223, v57 row_ror:8 row_mask:0xf bank_mask:0xf
	v_mov_b32_dpp v224, v58 row_ror:8 row_mask:0xf bank_mask:0xf
	v_mov_b32_dpp v225, v59 row_ror:8 row_mask:0xf bank_mask:0xf
	v_cndmask_b32_e32 v226, v222, v60, vcc
	v_cndmask_b32_e32 v227, v223, v61, vcc
	v_cndmask_b32_e32 v228, v224, v62, vcc
	v_cndmask_b32_e32 v229, v225, v63, vcc
	v_cndmask_b32_e32 v230, v60, v222, vcc
	v_cndmask_b32_e32 v231, v61, v223, vcc
	v_cndmask_b32_e32 v232, v62, v224, vcc
	v_cndmask_b32_e32 v233, v63, v225, vcc
	global_store_dwordx4 v236, v[226:229], s[72:73]
	global_store_dwordx4 v237, v[230:233], s[72:73]
	v_mov_b32_dpp v222, v44 row_ror:8 row_mask:0xf bank_mask:0xf
	v_mov_b32_dpp v223, v45 row_ror:8 row_mask:0xf bank_mask:0xf
	v_mov_b32_dpp v224, v46 row_ror:8 row_mask:0xf bank_mask:0xf
	v_mov_b32_dpp v225, v47 row_ror:8 row_mask:0xf bank_mask:0xf
	v_cndmask_b32_e32 v226, v222, v52, vcc
	v_cndmask_b32_e32 v227, v223, v53, vcc
	v_cndmask_b32_e32 v228, v224, v54, vcc
	v_cndmask_b32_e32 v229, v225, v55, vcc
	v_cndmask_b32_e32 v230, v52, v222, vcc
	v_cndmask_b32_e32 v231, v53, v223, vcc
	v_cndmask_b32_e32 v232, v54, v224, vcc
	v_cndmask_b32_e32 v233, v55, v225, vcc
	global_store_dwordx4 v236, v[226:229], s[72:73] offset:512
	global_store_dwordx4 v237, v[230:233], s[72:73] offset:512
	v_lshrrev_b32_e32 v236, 1, v164
	v_add_u32_e32 v236, v236, v245
	v_cvt_pk_bf16_f32 v194, v60, v61
	v_cvt_pk_bf16_f32 v195, v62, v63
	v_mul_f32_e32 v246, v61, v61
	v_mul_f32_e32 v247, v63, v63
	v_fmac_f32_e32 v246, v60, v60
	v_fmac_f32_e32 v247, v62, v62
	v_add_f32_e32 v184, v246, v247
	v_cvt_pk_bf16_f32 v196, v56, v57
	v_cvt_pk_bf16_f32 v197, v58, v59
	v_mul_f32_e32 v246, v57, v57
	v_mul_f32_e32 v247, v59, v59
	v_fmac_f32_e32 v246, v56, v56
	v_fmac_f32_e32 v247, v58, v58
	v_add_f32_e32 v246, v246, v247
	v_add_f32_e32 v184, v246, v184
	v_permlane16_swap_b32_e32 v194, v196
	v_permlane16_swap_b32_e32 v195, v197
	global_store_dwordx4 v236, v[194:197], s[22:23]
	s_nop 1
	v_cvt_pk_bf16_f32 v194, v52, v53
	v_cvt_pk_bf16_f32 v195, v54, v55
	v_mul_f32_e32 v246, v53, v53
	v_mul_f32_e32 v247, v55, v55
	v_fmac_f32_e32 v246, v52, v52
	v_fmac_f32_e32 v247, v54, v54
	v_add_f32_e32 v246, v246, v247
	v_add_f32_e32 v184, v246, v184
	v_cvt_pk_bf16_f32 v196, v44, v45
	v_cvt_pk_bf16_f32 v197, v46, v47
	v_mul_f32_e32 v246, v45, v45
	v_mul_f32_e32 v247, v47, v47
	v_fmac_f32_e32 v246, v44, v44
	v_fmac_f32_e32 v247, v46, v46
	v_add_f32_e32 v246, v246, v247
	v_add_f32_e32 v184, v246, v184
	v_permlane16_swap_b32_e32 v194, v196
	v_permlane16_swap_b32_e32 v195, v197
	global_store_dwordx4 v236, v[194:197], s[22:23] offset:256
	s_nop 1
	s_waitcnt vmcnt(26)
; __device__ __forceinline__ unsigned cvt_pk_bf16(float lo, float hi) { unsigned r; asm volatile("v_cvt_pk_bf16_f32 %0, %1, %2" : "=v"(r) : "v"(lo), "v"(hi)); return r; }
;     __device__ __forceinline__ void operator()(const f32x4 (&acc)[2][2][4][2], const Unit& u, int wr, int wc, int fr, int fq) const {
;     ...
;         for (int gi = 0; gi < 8; ++gi) {
;             const int ai = gi >> 2, m = gi & 3;
;             const int row = row0 + ai * HALF + m * 16;
;             const size_t off = (size_t)row * ldc + col0;
;             if (gi + 1 < 8) {
;                 const size_t offn = (size_t)(row0 + ((gi + 1) >> 2) * HALF + ((gi + 1) & 3) * 16) * ldc + col0;
; #pragma unroll
;                 for (int q = 0; q < 4; ++q) bs[(gi + 1) & 1][q] = *(const f32x4*)(xin + offn + (q >> 1) * HALF + (q & 1) * 16);
;             }
;             float sq = 0.f;
; #pragma unroll
;             for (int q = 0; q < 4; ++q) {
;                 const int bj = q >> 1, n = q & 1;
;                 const f32x4 o = bs[gi & 1][q] + acc[ai][bj][m][n];
;                 *(f32x4*)(out + off + bj * HALF + n * 16) = o;
;                 if (ss) {
;                     u32x2 w; w.x = cvt_pk_bf16(o[0], o[1]); w.y = cvt_pk_bf16(o[2], o[3]);
;                     *(u32x2*)(xb + off + bj * HALF + n * 16) = w;
;                     sq += (o[0] * o[0] + o[1] * o[1]) + (o[2] * o[2] + o[3] * o[3]);
;                 }
;             }
	v_mov_b32_dpp v222, v206 row_ror:8 row_mask:0xf bank_mask:0xf
	v_mov_b32_dpp v223, v207 row_ror:8 row_mask:0xf bank_mask:0xf
	v_mov_b32_dpp v224, v208 row_ror:8 row_mask:0xf bank_mask:0xf
	v_mov_b32_dpp v225, v209 row_ror:8 row_mask:0xf bank_mask:0xf
	v_mov_b32_dpp v226, v210 row_ror:8 row_mask:0xf bank_mask:0xf
	v_mov_b32_dpp v227, v211 row_ror:8 row_mask:0xf bank_mask:0xf
	v_mov_b32_dpp v228, v212 row_ror:8 row_mask:0xf bank_mask:0xf
	v_mov_b32_dpp v229, v213 row_ror:8 row_mask:0xf bank_mask:0xf
	v_cndmask_b32_e32 v230, v210, v206, vcc
	v_cndmask_b32_e32 v231, v211, v207, vcc
	v_cndmask_b32_e32 v232, v212, v208, vcc
	v_cndmask_b32_e32 v233, v213, v209, vcc
	v_cndmask_b32_e32 v222, v226, v222, vcc
	v_cndmask_b32_e32 v223, v227, v223, vcc
	v_cndmask_b32_e32 v224, v228, v224, vcc
	v_cndmask_b32_e32 v225, v229, v225, vcc
	v_pk_add_f32 v[48:49], v[230:231], v[48:49]
	v_pk_add_f32 v[50:51], v[232:233], v[50:51]
	v_pk_add_f32 v[40:41], v[222:223], v[40:41]
	v_pk_add_f32 v[42:43], v[224:225], v[42:43]
	v_mov_b32_dpp v222, v214 row_ror:8 row_mask:0xf bank_mask:0xf
	v_mov_b32_dpp v223, v215 row_ror:8 row_mask:0xf bank_mask:0xf
	v_mov_b32_dpp v224, v216 row_ror:8 row_mask:0xf bank_mask:0xf
	v_mov_b32_dpp v225, v217 row_ror:8 row_mask:0xf bank_mask:0xf
	v_mov_b32_dpp v226, v218 row_ror:8 row_mask:0xf bank_mask:0xf
	v_mov_b32_dpp v227, v219 row_ror:8 row_mask:0xf bank_mask:0xf
	v_mov_b32_dpp v228, v220 row_ror:8 row_mask:0xf bank_mask:0xf
	v_mov_b32_dpp v229, v221 row_ror:8 row_mask:0xf bank_mask:0xf
	v_cndmask_b32_e32 v230, v218, v214, vcc
	v_cndmask_b32_e32 v231, v219, v215, vcc
	v_cndmask_b32_e32 v232, v220, v216, vcc
	v_cndmask_b32_e32 v233, v221, v217, vcc
	v_cndmask_b32_e32 v222, v226, v222, vcc
	v_cndmask_b32_e32 v223, v227, v223, vcc
	v_cndmask_b32_e32 v224, v228, v224, vcc
	v_cndmask_b32_e32 v225, v229, v225, vcc
	v_pk_add_f32 v[36:37], v[230:231], v[36:37]
	v_pk_add_f32 v[38:39], v[232:233], v[38:39]
	v_pk_add_f32 v[28:29], v[222:223], v[28:29]
	v_pk_add_f32 v[30:31], v[224:225], v[30:31]
	v_add_u32_e32 v236, v165, v234
	v_add_u32_e32 v237, v165, v235
	v_mov_b32_dpp v222, v40 row_ror:8 row_mask:0xf bank_mask:0xf
	v_mov_b32_dpp v223, v41 row_ror:8 row_mask:0xf bank_mask:0xf
	v_mov_b32_dpp v224, v42 row_ror:8 row_mask:0xf bank_mask:0xf
	v_mov_b32_dpp v225, v43 row_ror:8 row_mask:0xf bank_mask:0xf
	v_cndmask_b32_e32 v226, v222, v48, vcc
	v_cndmask_b32_e32 v227, v223, v49, vcc
	v_cndmask_b32_e32 v228, v224, v50, vcc
	v_cndmask_b32_e32 v229, v225, v51, vcc
	v_cndmask_b32_e32 v230, v48, v222, vcc
	v_cndmask_b32_e32 v231, v49, v223, vcc
	v_cndmask_b32_e32 v232, v50, v224, vcc
	v_cndmask_b32_e32 v233, v51, v225, vcc
	global_store_dwordx4 v236, v[226:229], s[72:73]
	global_store_dwordx4 v237, v[230:233], s[72:73]
	v_mov_b32_dpp v222, v28 row_ror:8 row_mask:0xf bank_mask:0xf
	v_mov_b32_dpp v223, v29 row_ror:8 row_mask:0xf bank_mask:0xf
	v_mov_b32_dpp v224, v30 row_ror:8 row_mask:0xf bank_mask:0xf
	v_mov_b32_dpp v225, v31 row_ror:8 row_mask:0xf bank_mask:0xf
	v_cndmask_b32_e32 v226, v222, v36, vcc
	v_cndmask_b32_e32 v227, v223, v37, vcc
	v_cndmask_b32_e32 v228, v224, v38, vcc
	v_cndmask_b32_e32 v229, v225, v39, vcc
	v_cndmask_b32_e32 v230, v36, v222, vcc
	v_cndmask_b32_e32 v231, v37, v223, vcc
	v_cndmask_b32_e32 v232, v38, v224, vcc
	v_cndmask_b32_e32 v233, v39, v225, vcc
	global_store_dwordx4 v236, v[226:229], s[72:73] offset:512
	global_store_dwordx4 v237, v[230:233], s[72:73] offset:512
	v_lshrrev_b32_e32 v236, 1, v165
	v_add_u32_e32 v236, v236, v245
	v_cvt_pk_bf16_f32 v194, v48, v49
	v_cvt_pk_bf16_f32 v195, v50, v51
	v_mul_f32_e32 v246, v49, v49
	v_mul_f32_e32 v247, v51, v51
	v_fmac_f32_e32 v246, v48, v48
	v_fmac_f32_e32 v247, v50, v50
	v_add_f32_e32 v185, v246, v247
	v_cvt_pk_bf16_f32 v196, v40, v41
	v_cvt_pk_bf16_f32 v197, v42, v43
	v_mul_f32_e32 v246, v41, v41
	v_mul_f32_e32 v247, v43, v43
	v_fmac_f32_e32 v246, v40, v40
	v_fmac_f32_e32 v247, v42, v42
	v_add_f32_e32 v246, v246, v247
	v_add_f32_e32 v185, v246, v185
	v_permlane16_swap_b32_e32 v194, v196
	v_permlane16_swap_b32_e32 v195, v197
	global_store_dwordx4 v236, v[194:197], s[22:23]
	s_nop 1
	v_cvt_pk_bf16_f32 v194, v36, v37
	v_cvt_pk_bf16_f32 v195, v38, v39
	v_mul_f32_e32 v246, v37, v37
	v_mul_f32_e32 v247, v39, v39
	v_fmac_f32_e32 v246, v36, v36
	v_fmac_f32_e32 v247, v38, v38
	v_add_f32_e32 v246, v246, v247
	v_add_f32_e32 v185, v246, v185
	v_cvt_pk_bf16_f32 v196, v28, v29
	v_cvt_pk_bf16_f32 v197, v30, v31
	v_mul_f32_e32 v246, v29, v29
	v_mul_f32_e32 v247, v31, v31
	v_fmac_f32_e32 v246, v28, v28
	v_fmac_f32_e32 v247, v30, v30
	v_add_f32_e32 v246, v246, v247
	v_add_f32_e32 v185, v246, v185
	v_permlane16_swap_b32_e32 v194, v196
	v_permlane16_swap_b32_e32 v195, v197
	global_store_dwordx4 v236, v[194:197], s[22:23] offset:256
	s_nop 1
	s_waitcnt vmcnt(22)
; __device__ __forceinline__ unsigned cvt_pk_bf16(float lo, float hi) { unsigned r; asm volatile("v_cvt_pk_bf16_f32 %0, %1, %2" : "=v"(r) : "v"(lo), "v"(hi)); return r; }
;     __device__ __forceinline__ void operator()(const f32x4 (&acc)[2][2][4][2], const Unit& u, int wr, int wc, int fr, int fq) const {
;     ...
;         for (int gi = 0; gi < 8; ++gi) {
;             const int ai = gi >> 2, m = gi & 3;
;             const int row = row0 + ai * HALF + m * 16;
;             const size_t off = (size_t)row * ldc + col0;
;             if (gi + 1 < 8) {
;                 const size_t offn = (size_t)(row0 + ((gi + 1) >> 2) * HALF + ((gi + 1) & 3) * 16) * ldc + col0;
; #pragma unroll
;                 for (int q = 0; q < 4; ++q) bs[(gi + 1) & 1][q] = *(const f32x4*)(xin + offn + (q >> 1) * HALF + (q & 1) * 16);
;             }
;             float sq = 0.f;
; #pragma unroll
;             for (int q = 0; q < 4; ++q) {
;                 const int bj = q >> 1, n = q & 1;
;                 const f32x4 o = bs[gi & 1][q] + acc[ai][bj][m][n];
;                 *(f32x4*)(out + off + bj * HALF + n * 16) = o;
;                 if (ss) {
;                     u32x2 w; w.x = cvt_pk_bf16(o[0], o[1]); w.y = cvt_pk_bf16(o[2], o[3]);
;                     *(u32x2*)(xb + off + bj * HALF + n * 16) = w;
;                     sq += (o[0] * o[0] + o[1] * o[1]) + (o[2] * o[2] + o[3] * o[3]);
;                 }
;             }
	v_mov_b32_dpp v222, v128 row_ror:8 row_mask:0xf bank_mask:0xf
	v_mov_b32_dpp v223, v129 row_ror:8 row_mask:0xf bank_mask:0xf
	v_mov_b32_dpp v224, v130 row_ror:8 row_mask:0xf bank_mask:0xf
	v_mov_b32_dpp v225, v131 row_ror:8 row_mask:0xf bank_mask:0xf
	v_mov_b32_dpp v226, v132 row_ror:8 row_mask:0xf bank_mask:0xf
	v_mov_b32_dpp v227, v133 row_ror:8 row_mask:0xf bank_mask:0xf
	v_mov_b32_dpp v228, v134 row_ror:8 row_mask:0xf bank_mask:0xf
	v_mov_b32_dpp v229, v135 row_ror:8 row_mask:0xf bank_mask:0xf
	v_cndmask_b32_e32 v230, v132, v128, vcc
	v_cndmask_b32_e32 v231, v133, v129, vcc
	v_cndmask_b32_e32 v232, v134, v130, vcc
	v_cndmask_b32_e32 v233, v135, v131, vcc
	v_cndmask_b32_e32 v222, v226, v222, vcc
	v_cndmask_b32_e32 v223, v227, v223, vcc
	v_cndmask_b32_e32 v224, v228, v224, vcc
	v_cndmask_b32_e32 v225, v229, v225, vcc
	v_pk_add_f32 v[32:33], v[230:231], v[32:33]
	v_pk_add_f32 v[34:35], v[232:233], v[34:35]
	v_pk_add_f32 v[24:25], v[222:223], v[24:25]
	v_pk_add_f32 v[26:27], v[224:225], v[26:27]
	v_mov_b32_dpp v222, v136 row_ror:8 row_mask:0xf bank_mask:0xf
	v_mov_b32_dpp v223, v137 row_ror:8 row_mask:0xf bank_mask:0xf
	v_mov_b32_dpp v224, v138 row_ror:8 row_mask:0xf bank_mask:0xf
	v_mov_b32_dpp v225, v139 row_ror:8 row_mask:0xf bank_mask:0xf
	v_mov_b32_dpp v226, v140 row_ror:8 row_mask:0xf bank_mask:0xf
	v_mov_b32_dpp v227, v141 row_ror:8 row_mask:0xf bank_mask:0xf
	v_mov_b32_dpp v228, v142 row_ror:8 row_mask:0xf bank_mask:0xf
	v_mov_b32_dpp v229, v143 row_ror:8 row_mask:0xf bank_mask:0xf
	v_cndmask_b32_e32 v230, v140, v136, vcc
	v_cndmask_b32_e32 v231, v141, v137, vcc
	v_cndmask_b32_e32 v232, v142, v138, vcc
	v_cndmask_b32_e32 v233, v143, v139, vcc
	v_cndmask_b32_e32 v222, v226, v222, vcc
	v_cndmask_b32_e32 v223, v227, v223, vcc
	v_cndmask_b32_e32 v224, v228, v224, vcc
	v_cndmask_b32_e32 v225, v229, v225, vcc
	v_pk_add_f32 v[20:21], v[230:231], v[20:21]
	v_pk_add_f32 v[22:23], v[232:233], v[22:23]
	v_pk_add_f32 v[12:13], v[222:223], v[12:13]
	v_pk_add_f32 v[14:15], v[224:225], v[14:15]
	v_add_u32_e32 v236, v192, v234
	v_add_u32_e32 v237, v192, v235
	v_mov_b32_dpp v222, v24 row_ror:8 row_mask:0xf bank_mask:0xf
	v_mov_b32_dpp v223, v25 row_ror:8 row_mask:0xf bank_mask:0xf
	v_mov_b32_dpp v224, v26 row_ror:8 row_mask:0xf bank_mask:0xf
	v_mov_b32_dpp v225, v27 row_ror:8 row_mask:0xf bank_mask:0xf
	v_cndmask_b32_e32 v226, v222, v32, vcc
	v_cndmask_b32_e32 v227, v223, v33, vcc
	v_cndmask_b32_e32 v228, v224, v34, vcc
	v_cndmask_b32_e32 v229, v225, v35, vcc
	v_cndmask_b32_e32 v230, v32, v222, vcc
	v_cndmask_b32_e32 v231, v33, v223, vcc
	v_cndmask_b32_e32 v232, v34, v224, vcc
	v_cndmask_b32_e32 v233, v35, v225, vcc
	global_store_dwordx4 v236, v[226:229], s[72:73]
	global_store_dwordx4 v237, v[230:233], s[72:73]
	v_mov_b32_dpp v222, v12 row_ror:8 row_mask:0xf bank_mask:0xf
	v_mov_b32_dpp v223, v13 row_ror:8 row_mask:0xf bank_mask:0xf
	v_mov_b32_dpp v224, v14 row_ror:8 row_mask:0xf bank_mask:0xf
	v_mov_b32_dpp v225, v15 row_ror:8 row_mask:0xf bank_mask:0xf
	v_cndmask_b32_e32 v226, v222, v20, vcc
	v_cndmask_b32_e32 v227, v223, v21, vcc
	v_cndmask_b32_e32 v228, v224, v22, vcc
	v_cndmask_b32_e32 v229, v225, v23, vcc
	v_cndmask_b32_e32 v230, v20, v222, vcc
	v_cndmask_b32_e32 v231, v21, v223, vcc
	v_cndmask_b32_e32 v232, v22, v224, vcc
	v_cndmask_b32_e32 v233, v23, v225, vcc
	global_store_dwordx4 v236, v[226:229], s[72:73] offset:512
	global_store_dwordx4 v237, v[230:233], s[72:73] offset:512
	v_lshrrev_b32_e32 v236, 1, v192
	v_add_u32_e32 v236, v236, v245
	v_cvt_pk_bf16_f32 v194, v32, v33
	v_cvt_pk_bf16_f32 v195, v34, v35
	v_mul_f32_e32 v246, v33, v33
	v_mul_f32_e32 v247, v35, v35
	v_fmac_f32_e32 v246, v32, v32
	v_fmac_f32_e32 v247, v34, v34
	v_add_f32_e32 v186, v246, v247
	v_cvt_pk_bf16_f32 v196, v24, v25
	v_cvt_pk_bf16_f32 v197, v26, v27
	v_mul_f32_e32 v246, v25, v25
	v_mul_f32_e32 v247, v27, v27
	v_fmac_f32_e32 v246, v24, v24
	v_fmac_f32_e32 v247, v26, v26
	v_add_f32_e32 v246, v246, v247
	v_add_f32_e32 v186, v246, v186
	v_permlane16_swap_b32_e32 v194, v196
	v_permlane16_swap_b32_e32 v195, v197
	global_store_dwordx4 v236, v[194:197], s[22:23]
	s_nop 1
	v_cvt_pk_bf16_f32 v194, v20, v21
	v_cvt_pk_bf16_f32 v195, v22, v23
	v_mul_f32_e32 v246, v21, v21
	v_mul_f32_e32 v247, v23, v23
	v_fmac_f32_e32 v246, v20, v20
	v_fmac_f32_e32 v247, v22, v22
	v_add_f32_e32 v246, v246, v247
	v_add_f32_e32 v186, v246, v186
	v_cvt_pk_bf16_f32 v196, v12, v13
	v_cvt_pk_bf16_f32 v197, v14, v15
	v_mul_f32_e32 v246, v13, v13
	v_mul_f32_e32 v247, v15, v15
	v_fmac_f32_e32 v246, v12, v12
	v_fmac_f32_e32 v247, v14, v14
	v_add_f32_e32 v246, v246, v247
	v_add_f32_e32 v186, v246, v186
	v_permlane16_swap_b32_e32 v194, v196
	v_permlane16_swap_b32_e32 v195, v197
	global_store_dwordx4 v236, v[194:197], s[22:23] offset:256
	s_nop 1
	s_waitcnt vmcnt(18)
; __device__ __forceinline__ unsigned cvt_pk_bf16(float lo, float hi) { unsigned r; asm volatile("v_cvt_pk_bf16_f32 %0, %1, %2" : "=v"(r) : "v"(lo), "v"(hi)); return r; }
;     __device__ __forceinline__ void operator()(const f32x4 (&acc)[2][2][4][2], const Unit& u, int wr, int wc, int fr, int fq) const {
;     ...
;         for (int gi = 0; gi < 8; ++gi) {
;             const int ai = gi >> 2, m = gi & 3;
;             const int row = row0 + ai * HALF + m * 16;
;             const size_t off = (size_t)row * ldc + col0;
;             if (gi + 1 < 8) {
;                 const size_t offn = (size_t)(row0 + ((gi + 1) >> 2) * HALF + ((gi + 1) & 3) * 16) * ldc + col0;
; #pragma unroll
;                 for (int q = 0; q < 4; ++q) bs[(gi + 1) & 1][q] = *(const f32x4*)(xin + offn + (q >> 1) * HALF + (q & 1) * 16);
;             }
;             float sq = 0.f;
; #pragma unroll
;             for (int q = 0; q < 4; ++q) {
;                 const int bj = q >> 1, n = q & 1;
;                 const f32x4 o = bs[gi & 1][q] + acc[ai][bj][m][n];
;                 *(f32x4*)(out + off + bj * HALF + n * 16) = o;
;                 if (ss) {
;                     u32x2 w; w.x = cvt_pk_bf16(o[0], o[1]); w.y = cvt_pk_bf16(o[2], o[3]);
;                     *(u32x2*)(xb + off + bj * HALF + n * 16) = w;
;                     sq += (o[0] * o[0] + o[1] * o[1]) + (o[2] * o[2] + o[3] * o[3]);
;                 }
;             }
;             if (ss) { sq += __shfl_xor(sq, 16); sq += __shfl_xor(sq, 32); if (fq == 0) ss[(size_t)row * 32 + u.pn * 4 + wc] = sq; }
	v_mov_b32_dpp v222, v144 row_ror:8 row_mask:0xf bank_mask:0xf
	v_mov_b32_dpp v223, v145 row_ror:8 row_mask:0xf bank_mask:0xf
	v_mov_b32_dpp v224, v146 row_ror:8 row_mask:0xf bank_mask:0xf
	v_mov_b32_dpp v225, v147 row_ror:8 row_mask:0xf bank_mask:0xf
	v_mov_b32_dpp v226, v148 row_ror:8 row_mask:0xf bank_mask:0xf
	v_mov_b32_dpp v227, v149 row_ror:8 row_mask:0xf bank_mask:0xf
	v_mov_b32_dpp v228, v150 row_ror:8 row_mask:0xf bank_mask:0xf
	v_mov_b32_dpp v229, v151 row_ror:8 row_mask:0xf bank_mask:0xf
	v_cndmask_b32_e32 v230, v148, v144, vcc
	v_cndmask_b32_e32 v231, v149, v145, vcc
	v_cndmask_b32_e32 v232, v150, v146, vcc
	v_cndmask_b32_e32 v233, v151, v147, vcc
	v_cndmask_b32_e32 v222, v226, v222, vcc
	v_cndmask_b32_e32 v223, v227, v223, vcc
	v_cndmask_b32_e32 v224, v228, v224, vcc
	v_cndmask_b32_e32 v225, v229, v225, vcc
	v_pk_add_f32 v[16:17], v[230:231], v[16:17]
	v_pk_add_f32 v[18:19], v[232:233], v[18:19]
	v_pk_add_f32 v[8:9], v[222:223], v[8:9]
	v_pk_add_f32 v[10:11], v[224:225], v[10:11]
	v_mov_b32_dpp v222, v152 row_ror:8 row_mask:0xf bank_mask:0xf
	v_mov_b32_dpp v223, v153 row_ror:8 row_mask:0xf bank_mask:0xf
	v_mov_b32_dpp v224, v154 row_ror:8 row_mask:0xf bank_mask:0xf
	v_mov_b32_dpp v225, v155 row_ror:8 row_mask:0xf bank_mask:0xf
	v_mov_b32_dpp v226, v156 row_ror:8 row_mask:0xf bank_mask:0xf
	v_mov_b32_dpp v227, v157 row_ror:8 row_mask:0xf bank_mask:0xf
	v_mov_b32_dpp v228, v158 row_ror:8 row_mask:0xf bank_mask:0xf
	v_mov_b32_dpp v229, v159 row_ror:8 row_mask:0xf bank_mask:0xf
	v_cndmask_b32_e32 v230, v156, v152, vcc
	v_cndmask_b32_e32 v231, v157, v153, vcc
	v_cndmask_b32_e32 v232, v158, v154, vcc
	v_cndmask_b32_e32 v233, v159, v155, vcc
	v_cndmask_b32_e32 v222, v226, v222, vcc
	v_cndmask_b32_e32 v223, v227, v223, vcc
	v_cndmask_b32_e32 v224, v228, v224, vcc
	v_cndmask_b32_e32 v225, v229, v225, vcc
	v_pk_add_f32 v[4:5], v[230:231], v[4:5]
	v_pk_add_f32 v[6:7], v[232:233], v[6:7]
	v_pk_add_f32 v[0:1], v[222:223], v[0:1]
	v_pk_add_f32 v[2:3], v[224:225], v[2:3]
	v_add_u32_e32 v236, v193, v234
	v_add_u32_e32 v237, v193, v235
	v_mov_b32_dpp v222, v8 row_ror:8 row_mask:0xf bank_mask:0xf
	v_mov_b32_dpp v223, v9 row_ror:8 row_mask:0xf bank_mask:0xf
	v_mov_b32_dpp v224, v10 row_ror:8 row_mask:0xf bank_mask:0xf
	v_mov_b32_dpp v225, v11 row_ror:8 row_mask:0xf bank_mask:0xf
	v_cndmask_b32_e32 v226, v222, v16, vcc
	v_cndmask_b32_e32 v227, v223, v17, vcc
	v_cndmask_b32_e32 v228, v224, v18, vcc
	v_cndmask_b32_e32 v229, v225, v19, vcc
	v_cndmask_b32_e32 v230, v16, v222, vcc
	v_cndmask_b32_e32 v231, v17, v223, vcc
	v_cndmask_b32_e32 v232, v18, v224, vcc
	v_cndmask_b32_e32 v233, v19, v225, vcc
	global_store_dwordx4 v236, v[226:229], s[72:73]
	global_store_dwordx4 v237, v[230:233], s[72:73]
	v_mov_b32_dpp v222, v0 row_ror:8 row_mask:0xf bank_mask:0xf
	v_mov_b32_dpp v223, v1 row_ror:8 row_mask:0xf bank_mask:0xf
	v_mov_b32_dpp v224, v2 row_ror:8 row_mask:0xf bank_mask:0xf
	v_mov_b32_dpp v225, v3 row_ror:8 row_mask:0xf bank_mask:0xf
	v_cndmask_b32_e32 v226, v222, v4, vcc
	v_cndmask_b32_e32 v227, v223, v5, vcc
	v_cndmask_b32_e32 v228, v224, v6, vcc
	v_cndmask_b32_e32 v229, v225, v7, vcc
	v_cndmask_b32_e32 v230, v4, v222, vcc
	v_cndmask_b32_e32 v231, v5, v223, vcc
	v_cndmask_b32_e32 v232, v6, v224, vcc
	v_cndmask_b32_e32 v233, v7, v225, vcc
	global_store_dwordx4 v236, v[226:229], s[72:73] offset:512
	global_store_dwordx4 v237, v[230:233], s[72:73] offset:512
	v_lshrrev_b32_e32 v236, 1, v193
	v_add_u32_e32 v236, v236, v245
	v_cvt_pk_bf16_f32 v194, v16, v17
	v_cvt_pk_bf16_f32 v195, v18, v19
	v_mul_f32_e32 v246, v17, v17
	v_mul_f32_e32 v247, v19, v19
	v_fmac_f32_e32 v246, v16, v16
	v_fmac_f32_e32 v247, v18, v18
	v_add_f32_e32 v187, v246, v247
	v_cvt_pk_bf16_f32 v196, v8, v9
	v_cvt_pk_bf16_f32 v197, v10, v11
	v_mul_f32_e32 v246, v9, v9
	v_mul_f32_e32 v247, v11, v11
	v_fmac_f32_e32 v246, v8, v8
	v_fmac_f32_e32 v247, v10, v10
	v_add_f32_e32 v246, v246, v247
	v_add_f32_e32 v187, v246, v187
	v_permlane16_swap_b32_e32 v194, v196
	v_permlane16_swap_b32_e32 v195, v197
	global_store_dwordx4 v236, v[194:197], s[22:23]
	s_nop 1
	v_cvt_pk_bf16_f32 v194, v4, v5
	v_cvt_pk_bf16_f32 v195, v6, v7
	v_mul_f32_e32 v246, v5, v5
	v_mul_f32_e32 v247, v7, v7
	v_fmac_f32_e32 v246, v4, v4
	v_fmac_f32_e32 v247, v6, v6
	v_add_f32_e32 v246, v246, v247
	v_add_f32_e32 v187, v246, v187
	v_cvt_pk_bf16_f32 v196, v0, v1
	v_cvt_pk_bf16_f32 v197, v2, v3
	v_mul_f32_e32 v246, v1, v1
	v_mul_f32_e32 v247, v3, v3
	v_fmac_f32_e32 v246, v0, v0
	v_fmac_f32_e32 v247, v2, v2
	v_add_f32_e32 v246, v246, v247
	v_add_f32_e32 v187, v246, v187
	v_permlane16_swap_b32_e32 v194, v196
	v_permlane16_swap_b32_e32 v195, v197
	global_store_dwordx4 v236, v[194:197], s[22:23] offset:256
	s_nop 1
	v_xor_b32_e32 v246, 16, v167
	v_xor_b32_e32 v247, 32, v167
	v_lshlrev_b32_e32 v246, 2, v246
	v_lshlrev_b32_e32 v247, 2, v247
	ds_bpermute_b32 v128, v246, v180
	ds_bpermute_b32 v129, v246, v181
	ds_bpermute_b32 v130, v246, v182
	ds_bpermute_b32 v131, v246, v183
	ds_bpermute_b32 v132, v246, v184
	ds_bpermute_b32 v133, v246, v185
	ds_bpermute_b32 v134, v246, v186
	ds_bpermute_b32 v135, v246, v187
	s_waitcnt lgkmcnt(0)
	v_add_f32_e32 v180, v180, v128
	v_add_f32_e32 v181, v181, v129
	v_add_f32_e32 v182, v182, v130
	v_add_f32_e32 v183, v183, v131
	v_add_f32_e32 v184, v184, v132
	v_add_f32_e32 v185, v185, v133
	v_add_f32_e32 v186, v186, v134
	v_add_f32_e32 v187, v187, v135
	ds_bpermute_b32 v128, v247, v180
	ds_bpermute_b32 v129, v247, v181
	ds_bpermute_b32 v130, v247, v182
	ds_bpermute_b32 v131, v247, v183
	ds_bpermute_b32 v132, v247, v184
	ds_bpermute_b32 v133, v247, v185
	ds_bpermute_b32 v134, v247, v186
	ds_bpermute_b32 v135, v247, v187
	s_waitcnt lgkmcnt(0)
	v_add_f32_e32 v180, v180, v128
	v_add_f32_e32 v181, v181, v129
	v_add_f32_e32 v182, v182, v130
	v_add_f32_e32 v183, v183, v131
	v_add_f32_e32 v184, v184, v132
	v_add_f32_e32 v185, v185, v133
	v_add_f32_e32 v186, v186, v134
	v_add_f32_e32 v187, v187, v135
	v_add_u32_e32 v136, 0x0, v189
	v_add_u32_e32 v137, 0x800, v189
	v_add_u32_e32 v138, 0x1000, v189
	v_add_u32_e32 v139, 0x1800, v189
	v_add_u32_e32 v140, 0x4000, v189
	v_add_u32_e32 v141, 0x4800, v189
	v_add_u32_e32 v142, 0x5000, v189
	v_add_u32_e32 v143, 0x5800, v189
	s_and_saveexec_b64 s[36:37], s[0:1]
	global_store_dword v136, v180, s[10:11]
	global_store_dword v137, v181, s[10:11]
	global_store_dword v138, v182, s[10:11]
	global_store_dword v139, v183, s[10:11]
	global_store_dword v140, v184, s[10:11]
	global_store_dword v141, v185, s[10:11]
	global_store_dword v142, v186, s[10:11]
	global_store_dword v143, v187, s[10:11]
	s_or_b64 exec, exec, s[36:37]
	s_branch .LBB0_385
;     __device__ __forceinline__ void operator()(const f32x4 (&acc)[2][2][4][2], const Unit& u, int wr, int wc, int fr, int fq) const {
;         const int row0 = u.pm * BM + wr * 64 + fr, col0 = u.pn * BM + wc * 32 + 4 * fq;
;         f32x4 bs[2][4];
; #pragma unroll
;         for (int q = 0; q < 4; ++q) bs[0][q] = *(const f32x4*)(xin + (size_t)row0 * ldc + col0 + (q >> 1) * HALF + (q & 1) * 16);
; #pragma unroll
;         for (int gi = 0; gi < 8; ++gi) {
;             const int ai = gi >> 2, m = gi & 3;
;             const int row = row0 + ai * HALF + m * 16;
;             const size_t off = (size_t)row * ldc + col0;
;             if (gi + 1 < 8) {
;                 const size_t offn = (size_t)(row0 + ((gi + 1) >> 2) * HALF + ((gi + 1) & 3) * 16) * ldc + col0;
; #pragma unroll
;                 for (int q = 0; q < 4; ++q) bs[(gi + 1) & 1][q] = *(const f32x4*)(xin + offn + (q >> 1) * HALF + (q & 1) * 16);
;             }
;             float sq = 0.f;
; #pragma unroll
;             for (int q = 0; q < 4; ++q) {
;                 const int bj = q >> 1, n = q & 1;
;                 const f32x4 o = bs[gi & 1][q] + acc[ai][bj][m][n];
;                 *(f32x4*)(out + off + bj * HALF + n * 16) = o;
.Lres_noss:
	v_lshl_add_u32 v246, s55, 8, v188
	v_lshl_or_b32 v247, s2, 8, v190
	v_lshlrev_b32_e32 v247, 2, v247
	v_lshl_add_u32 v160, v246, 13, v247
	v_add_u32_e32 v161, 0x20000, v160
	v_add_u32_e32 v162, 0x40000, v160
	v_add_u32_e32 v163, 0x60000, v160
	v_add_u32_e32 v164, 0x100000, v160
	v_add_u32_e32 v165, 0x120000, v160
	v_add_u32_e32 v192, 0x140000, v160
	v_add_u32_e32 v193, 0x160000, v160
	v_and_b32_e32 v246, 8, v188
	v_mov_b32_e32 v247, 0x10040
	v_cmp_eq_u32_e32 vcc, 0, v246
	v_mov_b32_e32 v246, 0xffff0040
	s_nop 0
	v_cndmask_b32_e32 v234, v246, v169, vcc
	v_cndmask_b32_e32 v235, 0, v247, vcc
	v_add_u32_e32 v236, v160, v234
	v_add_u32_e32 v237, v160, v235
	global_load_dwordx4 v[128:131], v236, s[14:15]
	global_load_dwordx4 v[132:135], v237, s[14:15]
	global_load_dwordx4 v[136:139], v236, s[14:15] offset:512
	global_load_dwordx4 v[140:143], v237, s[14:15] offset:512
	v_add_u32_e32 v236, v161, v234
	v_add_u32_e32 v237, v161, v235
	global_load_dwordx4 v[144:147], v236, s[14:15]
	global_load_dwordx4 v[148:151], v237, s[14:15]
	global_load_dwordx4 v[152:155], v236, s[14:15] offset:512
	global_load_dwordx4 v[156:159], v237, s[14:15] offset:512
	v_add_u32_e32 v236, v162, v234
	v_add_u32_e32 v237, v162, v235
	global_load_dwordx4 v[206:209], v236, s[14:15]
	global_load_dwordx4 v[210:213], v237, s[14:15]
	global_load_dwordx4 v[214:217], v236, s[14:15] offset:512
	global_load_dwordx4 v[218:221], v237, s[14:15] offset:512
	s_waitcnt vmcnt(8)
	v_mov_b32_dpp v222, v128 row_ror:8 row_mask:0xf bank_mask:0xf
	v_mov_b32_dpp v223, v129 row_ror:8 row_mask:0xf bank_mask:0xf
	v_mov_b32_dpp v224, v130 row_ror:8 row_mask:0xf bank_mask:0xf
	v_mov_b32_dpp v225, v131 row_ror:8 row_mask:0xf bank_mask:0xf
	v_mov_b32_dpp v226, v132 row_ror:8 row_mask:0xf bank_mask:0xf
	v_mov_b32_dpp v227, v133 row_ror:8 row_mask:0xf bank_mask:0xf
	v_mov_b32_dpp v228, v134 row_ror:8 row_mask:0xf bank_mask:0xf
	v_mov_b32_dpp v229, v135 row_ror:8 row_mask:0xf bank_mask:0xf
	v_cndmask_b32_e32 v230, v132, v128, vcc
	v_cndmask_b32_e32 v231, v133, v129, vcc
	v_cndmask_b32_e32 v232, v134, v130, vcc
	v_cndmask_b32_e32 v233, v135, v131, vcc
	v_cndmask_b32_e32 v222, v226, v222, vcc
	v_cndmask_b32_e32 v223, v227, v223, vcc
	v_cndmask_b32_e32 v224, v228, v224, vcc
	v_cndmask_b32_e32 v225, v229, v225, vcc
	v_pk_add_f32 v[124:125], v[230:231], v[124:125]
	v_pk_add_f32 v[126:127], v[232:233], v[126:127]
	v_pk_add_f32 v[120:121], v[222:223], v[120:121]
	v_pk_add_f32 v[122:123], v[224:225], v[122:123]
	v_mov_b32_dpp v222, v136 row_ror:8 row_mask:0xf bank_mask:0xf
	v_mov_b32_dpp v223, v137 row_ror:8 row_mask:0xf bank_mask:0xf
	v_mov_b32_dpp v224, v138 row_ror:8 row_mask:0xf bank_mask:0xf
	v_mov_b32_dpp v225, v139 row_ror:8 row_mask:0xf bank_mask:0xf
	v_mov_b32_dpp v226, v140 row_ror:8 row_mask:0xf bank_mask:0xf
	v_mov_b32_dpp v227, v141 row_ror:8 row_mask:0xf bank_mask:0xf
	v_mov_b32_dpp v228, v142 row_ror:8 row_mask:0xf bank_mask:0xf
	v_mov_b32_dpp v229, v143 row_ror:8 row_mask:0xf bank_mask:0xf
	v_cndmask_b32_e32 v230, v140, v136, vcc
	v_cndmask_b32_e32 v231, v141, v137, vcc
	v_cndmask_b32_e32 v232, v142, v138, vcc
	v_cndmask_b32_e32 v233, v143, v139, vcc
	v_cndmask_b32_e32 v222, v226, v222, vcc
	v_cndmask_b32_e32 v223, v227, v223, vcc
	v_cndmask_b32_e32 v224, v228, v224, vcc
	v_cndmask_b32_e32 v225, v229, v225, vcc
	v_pk_add_f32 v[116:117], v[230:231], v[116:117]
	v_pk_add_f32 v[118:119], v[232:233], v[118:119]
	v_pk_add_f32 v[108:109], v[222:223], v[108:109]
	v_pk_add_f32 v[110:111], v[224:225], v[110:111]
	v_add_u32_e32 v236, v163, v234
	v_add_u32_e32 v237, v163, v235
	global_load_dwordx4 v[128:131], v236, s[14:15]
	global_load_dwordx4 v[132:135], v237, s[14:15]
	global_load_dwordx4 v[136:139], v236, s[14:15] offset:512
	global_load_dwordx4 v[140:143], v237, s[14:15] offset:512
	v_add_u32_e32 v236, v160, v234
	v_add_u32_e32 v237, v160, v235
	v_mov_b32_dpp v222, v120 row_ror:8 row_mask:0xf bank_mask:0xf
	v_mov_b32_dpp v223, v121 row_ror:8 row_mask:0xf bank_mask:0xf
	v_mov_b32_dpp v224, v122 row_ror:8 row_mask:0xf bank_mask:0xf
	v_mov_b32_dpp v225, v123 row_ror:8 row_mask:0xf bank_mask:0xf
	v_cndmask_b32_e32 v226, v222, v124, vcc
	v_cndmask_b32_e32 v227, v223, v125, vcc
	v_cndmask_b32_e32 v228, v224, v126, vcc
	v_cndmask_b32_e32 v229, v225, v127, vcc
	v_cndmask_b32_e32 v230, v124, v222, vcc
	v_cndmask_b32_e32 v231, v125, v223, vcc
	v_cndmask_b32_e32 v232, v126, v224, vcc
	v_cndmask_b32_e32 v233, v127, v225, vcc
	global_store_dwordx4 v236, v[226:229], s[72:73]
	global_store_dwordx4 v237, v[230:233], s[72:73]
	v_mov_b32_dpp v222, v108 row_ror:8 row_mask:0xf bank_mask:0xf
	v_mov_b32_dpp v223, v109 row_ror:8 row_mask:0xf bank_mask:0xf
	v_mov_b32_dpp v224, v110 row_ror:8 row_mask:0xf bank_mask:0xf
	v_mov_b32_dpp v225, v111 row_ror:8 row_mask:0xf bank_mask:0xf
	v_cndmask_b32_e32 v226, v222, v116, vcc
	v_cndmask_b32_e32 v227, v223, v117, vcc
	v_cndmask_b32_e32 v228, v224, v118, vcc
	v_cndmask_b32_e32 v229, v225, v119, vcc
	v_cndmask_b32_e32 v230, v116, v222, vcc
	v_cndmask_b32_e32 v231, v117, v223, vcc
	v_cndmask_b32_e32 v232, v118, v224, vcc
	v_cndmask_b32_e32 v233, v119, v225, vcc
	global_store_dwordx4 v236, v[226:229], s[72:73] offset:512
	global_store_dwordx4 v237, v[230:233], s[72:73] offset:512
	s_waitcnt vmcnt(12)
;     __device__ __forceinline__ void operator()(const f32x4 (&acc)[2][2][4][2], const Unit& u, int wr, int wc, int fr, int fq) const {
;     ...
;         for (int gi = 0; gi < 8; ++gi) {
;             const int ai = gi >> 2, m = gi & 3;
;             const int row = row0 + ai * HALF + m * 16;
;             const size_t off = (size_t)row * ldc + col0;
;             if (gi + 1 < 8) {
;                 const size_t offn = (size_t)(row0 + ((gi + 1) >> 2) * HALF + ((gi + 1) & 3) * 16) * ldc + col0;
; #pragma unroll
;                 for (int q = 0; q < 4; ++q) bs[(gi + 1) & 1][q] = *(const f32x4*)(xin + offn + (q >> 1) * HALF + (q & 1) * 16);
;             }
;             float sq = 0.f;
; #pragma unroll
;             for (int q = 0; q < 4; ++q) {
;                 const int bj = q >> 1, n = q & 1;
;                 const f32x4 o = bs[gi & 1][q] + acc[ai][bj][m][n];
;                 *(f32x4*)(out + off + bj * HALF + n * 16) = o;
	v_mov_b32_dpp v222, v144 row_ror:8 row_mask:0xf bank_mask:0xf
	v_mov_b32_dpp v223, v145 row_ror:8 row_mask:0xf bank_mask:0xf
	v_mov_b32_dpp v224, v146 row_ror:8 row_mask:0xf bank_mask:0xf
	v_mov_b32_dpp v225, v147 row_ror:8 row_mask:0xf bank_mask:0xf
	v_mov_b32_dpp v226, v148 row_ror:8 row_mask:0xf bank_mask:0xf
	v_mov_b32_dpp v227, v149 row_ror:8 row_mask:0xf bank_mask:0xf
	v_mov_b32_dpp v228, v150 row_ror:8 row_mask:0xf bank_mask:0xf
	v_mov_b32_dpp v229, v151 row_ror:8 row_mask:0xf bank_mask:0xf
	v_cndmask_b32_e32 v230, v148, v144, vcc
	v_cndmask_b32_e32 v231, v149, v145, vcc
	v_cndmask_b32_e32 v232, v150, v146, vcc
	v_cndmask_b32_e32 v233, v151, v147, vcc
	v_cndmask_b32_e32 v222, v226, v222, vcc
	v_cndmask_b32_e32 v223, v227, v223, vcc
	v_cndmask_b32_e32 v224, v228, v224, vcc
	v_cndmask_b32_e32 v225, v229, v225, vcc
	v_pk_add_f32 v[112:113], v[230:231], v[112:113]
	v_pk_add_f32 v[114:115], v[232:233], v[114:115]
	v_pk_add_f32 v[104:105], v[222:223], v[104:105]
	v_pk_add_f32 v[106:107], v[224:225], v[106:107]
	v_mov_b32_dpp v222, v152 row_ror:8 row_mask:0xf bank_mask:0xf
	v_mov_b32_dpp v223, v153 row_ror:8 row_mask:0xf bank_mask:0xf
	v_mov_b32_dpp v224, v154 row_ror:8 row_mask:0xf bank_mask:0xf
	v_mov_b32_dpp v225, v155 row_ror:8 row_mask:0xf bank_mask:0xf
	v_mov_b32_dpp v226, v156 row_ror:8 row_mask:0xf bank_mask:0xf
	v_mov_b32_dpp v227, v157 row_ror:8 row_mask:0xf bank_mask:0xf
	v_mov_b32_dpp v228, v158 row_ror:8 row_mask:0xf bank_mask:0xf
	v_mov_b32_dpp v229, v159 row_ror:8 row_mask:0xf bank_mask:0xf
	v_cndmask_b32_e32 v230, v156, v152, vcc
	v_cndmask_b32_e32 v231, v157, v153, vcc
	v_cndmask_b32_e32 v232, v158, v154, vcc
	v_cndmask_b32_e32 v233, v159, v155, vcc
	v_cndmask_b32_e32 v222, v226, v222, vcc
	v_cndmask_b32_e32 v223, v227, v223, vcc
	v_cndmask_b32_e32 v224, v228, v224, vcc
	v_cndmask_b32_e32 v225, v229, v225, vcc
	v_pk_add_f32 v[100:101], v[230:231], v[100:101]
	v_pk_add_f32 v[102:103], v[232:233], v[102:103]
	v_pk_add_f32 v[92:93], v[222:223], v[92:93]
	v_pk_add_f32 v[94:95], v[224:225], v[94:95]
	v_add_u32_e32 v236, v164, v234
	v_add_u32_e32 v237, v164, v235
	global_load_dwordx4 v[144:147], v236, s[14:15]
	global_load_dwordx4 v[148:151], v237, s[14:15]
	global_load_dwordx4 v[152:155], v236, s[14:15] offset:512
	global_load_dwordx4 v[156:159], v237, s[14:15] offset:512
	v_add_u32_e32 v236, v161, v234
	v_add_u32_e32 v237, v161, v235
	v_mov_b32_dpp v222, v104 row_ror:8 row_mask:0xf bank_mask:0xf
	v_mov_b32_dpp v223, v105 row_ror:8 row_mask:0xf bank_mask:0xf
	v_mov_b32_dpp v224, v106 row_ror:8 row_mask:0xf bank_mask:0xf
	v_mov_b32_dpp v225, v107 row_ror:8 row_mask:0xf bank_mask:0xf
	v_cndmask_b32_e32 v226, v222, v112, vcc
	v_cndmask_b32_e32 v227, v223, v113, vcc
	v_cndmask_b32_e32 v228, v224, v114, vcc
	v_cndmask_b32_e32 v229, v225, v115, vcc
	v_cndmask_b32_e32 v230, v112, v222, vcc
	v_cndmask_b32_e32 v231, v113, v223, vcc
	v_cndmask_b32_e32 v232, v114, v224, vcc
	v_cndmask_b32_e32 v233, v115, v225, vcc
	global_store_dwordx4 v236, v[226:229], s[72:73]
	global_store_dwordx4 v237, v[230:233], s[72:73]
	v_mov_b32_dpp v222, v92 row_ror:8 row_mask:0xf bank_mask:0xf
	v_mov_b32_dpp v223, v93 row_ror:8 row_mask:0xf bank_mask:0xf
	v_mov_b32_dpp v224, v94 row_ror:8 row_mask:0xf bank_mask:0xf
	v_mov_b32_dpp v225, v95 row_ror:8 row_mask:0xf bank_mask:0xf
	v_cndmask_b32_e32 v226, v222, v100, vcc
	v_cndmask_b32_e32 v227, v223, v101, vcc
	v_cndmask_b32_e32 v228, v224, v102, vcc
	v_cndmask_b32_e32 v229, v225, v103, vcc
	v_cndmask_b32_e32 v230, v100, v222, vcc
	v_cndmask_b32_e32 v231, v101, v223, vcc
	v_cndmask_b32_e32 v232, v102, v224, vcc
	v_cndmask_b32_e32 v233, v103, v225, vcc
	global_store_dwordx4 v236, v[226:229], s[72:73] offset:512
	global_store_dwordx4 v237, v[230:233], s[72:73] offset:512
	s_waitcnt vmcnt(16)
	v_mov_b32_dpp v222, v206 row_ror:8 row_mask:0xf bank_mask:0xf
	v_mov_b32_dpp v223, v207 row_ror:8 row_mask:0xf bank_mask:0xf
	v_mov_b32_dpp v224, v208 row_ror:8 row_mask:0xf bank_mask:0xf
	v_mov_b32_dpp v225, v209 row_ror:8 row_mask:0xf bank_mask:0xf
	v_mov_b32_dpp v226, v210 row_ror:8 row_mask:0xf bank_mask:0xf
	v_mov_b32_dpp v227, v211 row_ror:8 row_mask:0xf bank_mask:0xf
	v_mov_b32_dpp v228, v212 row_ror:8 row_mask:0xf bank_mask:0xf
	v_mov_b32_dpp v229, v213 row_ror:8 row_mask:0xf bank_mask:0xf
	v_cndmask_b32_e32 v230, v210, v206, vcc
	v_cndmask_b32_e32 v231, v211, v207, vcc
	v_cndmask_b32_e32 v232, v212, v208, vcc
	v_cndmask_b32_e32 v233, v213, v209, vcc
	v_cndmask_b32_e32 v222, v226, v222, vcc
	v_cndmask_b32_e32 v223, v227, v223, vcc
	v_cndmask_b32_e32 v224, v228, v224, vcc
	v_cndmask_b32_e32 v225, v229, v225, vcc
	v_pk_add_f32 v[96:97], v[230:231], v[96:97]
	v_pk_add_f32 v[98:99], v[232:233], v[98:99]
	v_pk_add_f32 v[88:89], v[222:223], v[88:89]
	v_pk_add_f32 v[90:91], v[224:225], v[90:91]
	v_mov_b32_dpp v222, v214 row_ror:8 row_mask:0xf bank_mask:0xf
	v_mov_b32_dpp v223, v215 row_ror:8 row_mask:0xf bank_mask:0xf
	v_mov_b32_dpp v224, v216 row_ror:8 row_mask:0xf bank_mask:0xf
	v_mov_b32_dpp v225, v217 row_ror:8 row_mask:0xf bank_mask:0xf
	v_mov_b32_dpp v226, v218 row_ror:8 row_mask:0xf bank_mask:0xf
	v_mov_b32_dpp v227, v219 row_ror:8 row_mask:0xf bank_mask:0xf
	v_mov_b32_dpp v228, v220 row_ror:8 row_mask:0xf bank_mask:0xf
	v_mov_b32_dpp v229, v221 row_ror:8 row_mask:0xf bank_mask:0xf
	v_cndmask_b32_e32 v230, v218, v214, vcc
	v_cndmask_b32_e32 v231, v219, v215, vcc
	v_cndmask_b32_e32 v232, v220, v216, vcc
	v_cndmask_b32_e32 v233, v221, v217, vcc
	v_cndmask_b32_e32 v222, v226, v222, vcc
	v_cndmask_b32_e32 v223, v227, v223, vcc
	v_cndmask_b32_e32 v224, v228, v224, vcc
	v_cndmask_b32_e32 v225, v229, v225, vcc
;     __device__ __forceinline__ void operator()(const f32x4 (&acc)[2][2][4][2], const Unit& u, int wr, int wc, int fr, int fq) const {
;     ...
;         for (int gi = 0; gi < 8; ++gi) {
;             const int ai = gi >> 2, m = gi & 3;
;             const int row = row0 + ai * HALF + m * 16;
;             const size_t off = (size_t)row * ldc + col0;
;             if (gi + 1 < 8) {
;                 const size_t offn = (size_t)(row0 + ((gi + 1) >> 2) * HALF + ((gi + 1) & 3) * 16) * ldc + col0;
; #pragma unroll
;                 for (int q = 0; q < 4; ++q) bs[(gi + 1) & 1][q] = *(const f32x4*)(xin + offn + (q >> 1) * HALF + (q & 1) * 16);
;             }
;             float sq = 0.f;
; #pragma unroll
;             for (int q = 0; q < 4; ++q) {
;                 const int bj = q >> 1, n = q & 1;
;                 const f32x4 o = bs[gi & 1][q] + acc[ai][bj][m][n];
;                 *(f32x4*)(out + off + bj * HALF + n * 16) = o;
	v_pk_add_f32 v[84:85], v[230:231], v[84:85]
	v_pk_add_f32 v[86:87], v[232:233], v[86:87]
	v_pk_add_f32 v[76:77], v[222:223], v[76:77]
	v_pk_add_f32 v[78:79], v[224:225], v[78:79]
	v_add_u32_e32 v236, v165, v234
	v_add_u32_e32 v237, v165, v235
	global_load_dwordx4 v[206:209], v236, s[14:15]
	global_load_dwordx4 v[210:213], v237, s[14:15]
	global_load_dwordx4 v[214:217], v236, s[14:15] offset:512
	global_load_dwordx4 v[218:221], v237, s[14:15] offset:512
	v_add_u32_e32 v236, v162, v234
	v_add_u32_e32 v237, v162, v235
	v_mov_b32_dpp v222, v88 row_ror:8 row_mask:0xf bank_mask:0xf
	v_mov_b32_dpp v223, v89 row_ror:8 row_mask:0xf bank_mask:0xf
	v_mov_b32_dpp v224, v90 row_ror:8 row_mask:0xf bank_mask:0xf
	v_mov_b32_dpp v225, v91 row_ror:8 row_mask:0xf bank_mask:0xf
	v_cndmask_b32_e32 v226, v222, v96, vcc
	v_cndmask_b32_e32 v227, v223, v97, vcc
	v_cndmask_b32_e32 v228, v224, v98, vcc
	v_cndmask_b32_e32 v229, v225, v99, vcc
	v_cndmask_b32_e32 v230, v96, v222, vcc
	v_cndmask_b32_e32 v231, v97, v223, vcc
	v_cndmask_b32_e32 v232, v98, v224, vcc
	v_cndmask_b32_e32 v233, v99, v225, vcc
	global_store_dwordx4 v236, v[226:229], s[72:73]
	global_store_dwordx4 v237, v[230:233], s[72:73]
	v_mov_b32_dpp v222, v76 row_ror:8 row_mask:0xf bank_mask:0xf
	v_mov_b32_dpp v223, v77 row_ror:8 row_mask:0xf bank_mask:0xf
	v_mov_b32_dpp v224, v78 row_ror:8 row_mask:0xf bank_mask:0xf
	v_mov_b32_dpp v225, v79 row_ror:8 row_mask:0xf bank_mask:0xf
	v_cndmask_b32_e32 v226, v222, v84, vcc
	v_cndmask_b32_e32 v227, v223, v85, vcc
	v_cndmask_b32_e32 v228, v224, v86, vcc
	v_cndmask_b32_e32 v229, v225, v87, vcc
	v_cndmask_b32_e32 v230, v84, v222, vcc
	v_cndmask_b32_e32 v231, v85, v223, vcc
	v_cndmask_b32_e32 v232, v86, v224, vcc
	v_cndmask_b32_e32 v233, v87, v225, vcc
	global_store_dwordx4 v236, v[226:229], s[72:73] offset:512
	global_store_dwordx4 v237, v[230:233], s[72:73] offset:512
	s_waitcnt vmcnt(20)
	v_mov_b32_dpp v222, v128 row_ror:8 row_mask:0xf bank_mask:0xf
	v_mov_b32_dpp v223, v129 row_ror:8 row_mask:0xf bank_mask:0xf
	v_mov_b32_dpp v224, v130 row_ror:8 row_mask:0xf bank_mask:0xf
	v_mov_b32_dpp v225, v131 row_ror:8 row_mask:0xf bank_mask:0xf
	v_mov_b32_dpp v226, v132 row_ror:8 row_mask:0xf bank_mask:0xf
	v_mov_b32_dpp v227, v133 row_ror:8 row_mask:0xf bank_mask:0xf
	v_mov_b32_dpp v228, v134 row_ror:8 row_mask:0xf bank_mask:0xf
	v_mov_b32_dpp v229, v135 row_ror:8 row_mask:0xf bank_mask:0xf
	v_cndmask_b32_e32 v230, v132, v128, vcc
	v_cndmask_b32_e32 v231, v133, v129, vcc
	v_cndmask_b32_e32 v232, v134, v130, vcc
	v_cndmask_b32_e32 v233, v135, v131, vcc
	v_cndmask_b32_e32 v222, v226, v222, vcc
	v_cndmask_b32_e32 v223, v227, v223, vcc
	v_cndmask_b32_e32 v224, v228, v224, vcc
	v_cndmask_b32_e32 v225, v229, v225, vcc
	v_pk_add_f32 v[80:81], v[230:231], v[80:81]
	v_pk_add_f32 v[82:83], v[232:233], v[82:83]
	v_pk_add_f32 v[72:73], v[222:223], v[72:73]
	v_pk_add_f32 v[74:75], v[224:225], v[74:75]
	v_mov_b32_dpp v222, v136 row_ror:8 row_mask:0xf bank_mask:0xf
	v_mov_b32_dpp v223, v137 row_ror:8 row_mask:0xf bank_mask:0xf
	v_mov_b32_dpp v224, v138 row_ror:8 row_mask:0xf bank_mask:0xf
	v_mov_b32_dpp v225, v139 row_ror:8 row_mask:0xf bank_mask:0xf
	v_mov_b32_dpp v226, v140 row_ror:8 row_mask:0xf bank_mask:0xf
	v_mov_b32_dpp v227, v141 row_ror:8 row_mask:0xf bank_mask:0xf
	v_mov_b32_dpp v228, v142 row_ror:8 row_mask:0xf bank_mask:0xf
	v_mov_b32_dpp v229, v143 row_ror:8 row_mask:0xf bank_mask:0xf
	v_cndmask_b32_e32 v230, v140, v136, vcc
	v_cndmask_b32_e32 v231, v141, v137, vcc
	v_cndmask_b32_e32 v232, v142, v138, vcc
	v_cndmask_b32_e32 v233, v143, v139, vcc
	v_cndmask_b32_e32 v222, v226, v222, vcc
	v_cndmask_b32_e32 v223, v227, v223, vcc
	v_cndmask_b32_e32 v224, v228, v224, vcc
	v_cndmask_b32_e32 v225, v229, v225, vcc
	v_pk_add_f32 v[68:69], v[230:231], v[68:69]
	v_pk_add_f32 v[70:71], v[232:233], v[70:71]
	v_pk_add_f32 v[64:65], v[222:223], v[64:65]
	v_pk_add_f32 v[66:67], v[224:225], v[66:67]
	v_add_u32_e32 v236, v192, v234
	v_add_u32_e32 v237, v192, v235
	global_load_dwordx4 v[128:131], v236, s[14:15]
	global_load_dwordx4 v[132:135], v237, s[14:15]
	global_load_dwordx4 v[136:139], v236, s[14:15] offset:512
	global_load_dwordx4 v[140:143], v237, s[14:15] offset:512
	v_add_u32_e32 v236, v163, v234
	v_add_u32_e32 v237, v163, v235
	v_mov_b32_dpp v222, v72 row_ror:8 row_mask:0xf bank_mask:0xf
	v_mov_b32_dpp v223, v73 row_ror:8 row_mask:0xf bank_mask:0xf
	v_mov_b32_dpp v224, v74 row_ror:8 row_mask:0xf bank_mask:0xf
	v_mov_b32_dpp v225, v75 row_ror:8 row_mask:0xf bank_mask:0xf
	v_cndmask_b32_e32 v226, v222, v80, vcc
	v_cndmask_b32_e32 v227, v223, v81, vcc
	v_cndmask_b32_e32 v228, v224, v82, vcc
	v_cndmask_b32_e32 v229, v225, v83, vcc
	v_cndmask_b32_e32 v230, v80, v222, vcc
	v_cndmask_b32_e32 v231, v81, v223, vcc
	v_cndmask_b32_e32 v232, v82, v224, vcc
	v_cndmask_b32_e32 v233, v83, v225, vcc
	global_store_dwordx4 v236, v[226:229], s[72:73]
	global_store_dwordx4 v237, v[230:233], s[72:73]
	v_mov_b32_dpp v222, v64 row_ror:8 row_mask:0xf bank_mask:0xf
	v_mov_b32_dpp v223, v65 row_ror:8 row_mask:0xf bank_mask:0xf
	v_mov_b32_dpp v224, v66 row_ror:8 row_mask:0xf bank_mask:0xf
	v_mov_b32_dpp v225, v67 row_ror:8 row_mask:0xf bank_mask:0xf
	v_cndmask_b32_e32 v226, v222, v68, vcc
	v_cndmask_b32_e32 v227, v223, v69, vcc
	v_cndmask_b32_e32 v228, v224, v70, vcc
	v_cndmask_b32_e32 v229, v225, v71, vcc
	v_cndmask_b32_e32 v230, v68, v222, vcc
	v_cndmask_b32_e32 v231, v69, v223, vcc
	v_cndmask_b32_e32 v232, v70, v224, vcc
	v_cndmask_b32_e32 v233, v71, v225, vcc
	global_store_dwordx4 v236, v[226:229], s[72:73] offset:512
	global_store_dwordx4 v237, v[230:233], s[72:73] offset:512
	s_waitcnt vmcnt(20)
;     __device__ __forceinline__ void operator()(const f32x4 (&acc)[2][2][4][2], const Unit& u, int wr, int wc, int fr, int fq) const {
;     ...
;         for (int gi = 0; gi < 8; ++gi) {
;             const int ai = gi >> 2, m = gi & 3;
;             const int row = row0 + ai * HALF + m * 16;
;             const size_t off = (size_t)row * ldc + col0;
;             if (gi + 1 < 8) {
;                 const size_t offn = (size_t)(row0 + ((gi + 1) >> 2) * HALF + ((gi + 1) & 3) * 16) * ldc + col0;
; #pragma unroll
;                 for (int q = 0; q < 4; ++q) bs[(gi + 1) & 1][q] = *(const f32x4*)(xin + offn + (q >> 1) * HALF + (q & 1) * 16);
;             }
;             float sq = 0.f;
; #pragma unroll
;             for (int q = 0; q < 4; ++q) {
;                 const int bj = q >> 1, n = q & 1;
;                 const f32x4 o = bs[gi & 1][q] + acc[ai][bj][m][n];
;                 *(f32x4*)(out + off + bj * HALF + n * 16) = o;
	v_mov_b32_dpp v222, v144 row_ror:8 row_mask:0xf bank_mask:0xf
	v_mov_b32_dpp v223, v145 row_ror:8 row_mask:0xf bank_mask:0xf
	v_mov_b32_dpp v224, v146 row_ror:8 row_mask:0xf bank_mask:0xf
	v_mov_b32_dpp v225, v147 row_ror:8 row_mask:0xf bank_mask:0xf
	v_mov_b32_dpp v226, v148 row_ror:8 row_mask:0xf bank_mask:0xf
	v_mov_b32_dpp v227, v149 row_ror:8 row_mask:0xf bank_mask:0xf
	v_mov_b32_dpp v228, v150 row_ror:8 row_mask:0xf bank_mask:0xf
	v_mov_b32_dpp v229, v151 row_ror:8 row_mask:0xf bank_mask:0xf
	v_cndmask_b32_e32 v230, v148, v144, vcc
	v_cndmask_b32_e32 v231, v149, v145, vcc
	v_cndmask_b32_e32 v232, v150, v146, vcc
	v_cndmask_b32_e32 v233, v151, v147, vcc
	v_cndmask_b32_e32 v222, v226, v222, vcc
	v_cndmask_b32_e32 v223, v227, v223, vcc
	v_cndmask_b32_e32 v224, v228, v224, vcc
	v_cndmask_b32_e32 v225, v229, v225, vcc
	v_pk_add_f32 v[60:61], v[230:231], v[60:61]
	v_pk_add_f32 v[62:63], v[232:233], v[62:63]
	v_pk_add_f32 v[56:57], v[222:223], v[56:57]
	v_pk_add_f32 v[58:59], v[224:225], v[58:59]
	v_mov_b32_dpp v222, v152 row_ror:8 row_mask:0xf bank_mask:0xf
	v_mov_b32_dpp v223, v153 row_ror:8 row_mask:0xf bank_mask:0xf
	v_mov_b32_dpp v224, v154 row_ror:8 row_mask:0xf bank_mask:0xf
	v_mov_b32_dpp v225, v155 row_ror:8 row_mask:0xf bank_mask:0xf
	v_mov_b32_dpp v226, v156 row_ror:8 row_mask:0xf bank_mask:0xf
	v_mov_b32_dpp v227, v157 row_ror:8 row_mask:0xf bank_mask:0xf
	v_mov_b32_dpp v228, v158 row_ror:8 row_mask:0xf bank_mask:0xf
	v_mov_b32_dpp v229, v159 row_ror:8 row_mask:0xf bank_mask:0xf
	v_cndmask_b32_e32 v230, v156, v152, vcc
	v_cndmask_b32_e32 v231, v157, v153, vcc
	v_cndmask_b32_e32 v232, v158, v154, vcc
	v_cndmask_b32_e32 v233, v159, v155, vcc
	v_cndmask_b32_e32 v222, v226, v222, vcc
	v_cndmask_b32_e32 v223, v227, v223, vcc
	v_cndmask_b32_e32 v224, v228, v224, vcc
	v_cndmask_b32_e32 v225, v229, v225, vcc
	v_pk_add_f32 v[52:53], v[230:231], v[52:53]
	v_pk_add_f32 v[54:55], v[232:233], v[54:55]
	v_pk_add_f32 v[44:45], v[222:223], v[44:45]
	v_pk_add_f32 v[46:47], v[224:225], v[46:47]
	v_add_u32_e32 v236, v193, v234
	v_add_u32_e32 v237, v193, v235
	global_load_dwordx4 v[144:147], v236, s[14:15]
	global_load_dwordx4 v[148:151], v237, s[14:15]
	global_load_dwordx4 v[152:155], v236, s[14:15] offset:512
	global_load_dwordx4 v[156:159], v237, s[14:15] offset:512
	v_add_u32_e32 v236, v164, v234
	v_add_u32_e32 v237, v164, v235
	v_mov_b32_dpp v222, v56 row_ror:8 row_mask:0xf bank_mask:0xf
	v_mov_b32_dpp v223, v57 row_ror:8 row_mask:0xf bank_mask:0xf
	v_mov_b32_dpp v224, v58 row_ror:8 row_mask:0xf bank_mask:0xf
	v_mov_b32_dpp v225, v59 row_ror:8 row_mask:0xf bank_mask:0xf
	v_cndmask_b32_e32 v226, v222, v60, vcc
	v_cndmask_b32_e32 v227, v223, v61, vcc
	v_cndmask_b32_e32 v228, v224, v62, vcc
	v_cndmask_b32_e32 v229, v225, v63, vcc
	v_cndmask_b32_e32 v230, v60, v222, vcc
	v_cndmask_b32_e32 v231, v61, v223, vcc
	v_cndmask_b32_e32 v232, v62, v224, vcc
	v_cndmask_b32_e32 v233, v63, v225, vcc
	global_store_dwordx4 v236, v[226:229], s[72:73]
	global_store_dwordx4 v237, v[230:233], s[72:73]
	v_mov_b32_dpp v222, v44 row_ror:8 row_mask:0xf bank_mask:0xf
	v_mov_b32_dpp v223, v45 row_ror:8 row_mask:0xf bank_mask:0xf
	v_mov_b32_dpp v224, v46 row_ror:8 row_mask:0xf bank_mask:0xf
	v_mov_b32_dpp v225, v47 row_ror:8 row_mask:0xf bank_mask:0xf
	v_cndmask_b32_e32 v226, v222, v52, vcc
	v_cndmask_b32_e32 v227, v223, v53, vcc
	v_cndmask_b32_e32 v228, v224, v54, vcc
	v_cndmask_b32_e32 v229, v225, v55, vcc
	v_cndmask_b32_e32 v230, v52, v222, vcc
	v_cndmask_b32_e32 v231, v53, v223, vcc
	v_cndmask_b32_e32 v232, v54, v224, vcc
	v_cndmask_b32_e32 v233, v55, v225, vcc
	global_store_dwordx4 v236, v[226:229], s[72:73] offset:512
	global_store_dwordx4 v237, v[230:233], s[72:73] offset:512
	s_waitcnt vmcnt(20)
	v_mov_b32_dpp v222, v206 row_ror:8 row_mask:0xf bank_mask:0xf
	v_mov_b32_dpp v223, v207 row_ror:8 row_mask:0xf bank_mask:0xf
	v_mov_b32_dpp v224, v208 row_ror:8 row_mask:0xf bank_mask:0xf
	v_mov_b32_dpp v225, v209 row_ror:8 row_mask:0xf bank_mask:0xf
	v_mov_b32_dpp v226, v210 row_ror:8 row_mask:0xf bank_mask:0xf
	v_mov_b32_dpp v227, v211 row_ror:8 row_mask:0xf bank_mask:0xf
	v_mov_b32_dpp v228, v212 row_ror:8 row_mask:0xf bank_mask:0xf
	v_mov_b32_dpp v229, v213 row_ror:8 row_mask:0xf bank_mask:0xf
	v_cndmask_b32_e32 v230, v210, v206, vcc
	v_cndmask_b32_e32 v231, v211, v207, vcc
	v_cndmask_b32_e32 v232, v212, v208, vcc
	v_cndmask_b32_e32 v233, v213, v209, vcc
	v_cndmask_b32_e32 v222, v226, v222, vcc
	v_cndmask_b32_e32 v223, v227, v223, vcc
	v_cndmask_b32_e32 v224, v228, v224, vcc
	v_cndmask_b32_e32 v225, v229, v225, vcc
	v_pk_add_f32 v[48:49], v[230:231], v[48:49]
	v_pk_add_f32 v[50:51], v[232:233], v[50:51]
	v_pk_add_f32 v[40:41], v[222:223], v[40:41]
	v_pk_add_f32 v[42:43], v[224:225], v[42:43]
	v_mov_b32_dpp v222, v214 row_ror:8 row_mask:0xf bank_mask:0xf
	v_mov_b32_dpp v223, v215 row_ror:8 row_mask:0xf bank_mask:0xf
	v_mov_b32_dpp v224, v216 row_ror:8 row_mask:0xf bank_mask:0xf
	v_mov_b32_dpp v225, v217 row_ror:8 row_mask:0xf bank_mask:0xf
	v_mov_b32_dpp v226, v218 row_ror:8 row_mask:0xf bank_mask:0xf
	v_mov_b32_dpp v227, v219 row_ror:8 row_mask:0xf bank_mask:0xf
	v_mov_b32_dpp v228, v220 row_ror:8 row_mask:0xf bank_mask:0xf
	v_mov_b32_dpp v229, v221 row_ror:8 row_mask:0xf bank_mask:0xf
	v_cndmask_b32_e32 v230, v218, v214, vcc
	v_cndmask_b32_e32 v231, v219, v215, vcc
	v_cndmask_b32_e32 v232, v220, v216, vcc
	v_cndmask_b32_e32 v233, v221, v217, vcc
	v_cndmask_b32_e32 v222, v226, v222, vcc
	v_cndmask_b32_e32 v223, v227, v223, vcc
	v_cndmask_b32_e32 v224, v228, v224, vcc
	v_cndmask_b32_e32 v225, v229, v225, vcc
	v_pk_add_f32 v[36:37], v[230:231], v[36:37]
;     __device__ __forceinline__ void operator()(const f32x4 (&acc)[2][2][4][2], const Unit& u, int wr, int wc, int fr, int fq) const {
;     ...
;         for (int gi = 0; gi < 8; ++gi) {
;             const int ai = gi >> 2, m = gi & 3;
;             const int row = row0 + ai * HALF + m * 16;
;             const size_t off = (size_t)row * ldc + col0;
;             if (gi + 1 < 8) {
;                 const size_t offn = (size_t)(row0 + ((gi + 1) >> 2) * HALF + ((gi + 1) & 3) * 16) * ldc + col0;
; #pragma unroll
;                 for (int q = 0; q < 4; ++q) bs[(gi + 1) & 1][q] = *(const f32x4*)(xin + offn + (q >> 1) * HALF + (q & 1) * 16);
;             }
;             float sq = 0.f;
; #pragma unroll
;             for (int q = 0; q < 4; ++q) {
;                 const int bj = q >> 1, n = q & 1;
;                 const f32x4 o = bs[gi & 1][q] + acc[ai][bj][m][n];
;                 *(f32x4*)(out + off + bj * HALF + n * 16) = o;
	v_pk_add_f32 v[38:39], v[232:233], v[38:39]
	v_pk_add_f32 v[28:29], v[222:223], v[28:29]
	v_pk_add_f32 v[30:31], v[224:225], v[30:31]
	v_add_u32_e32 v236, v165, v234
	v_add_u32_e32 v237, v165, v235
	v_mov_b32_dpp v222, v40 row_ror:8 row_mask:0xf bank_mask:0xf
	v_mov_b32_dpp v223, v41 row_ror:8 row_mask:0xf bank_mask:0xf
	v_mov_b32_dpp v224, v42 row_ror:8 row_mask:0xf bank_mask:0xf
	v_mov_b32_dpp v225, v43 row_ror:8 row_mask:0xf bank_mask:0xf
	v_cndmask_b32_e32 v226, v222, v48, vcc
	v_cndmask_b32_e32 v227, v223, v49, vcc
	v_cndmask_b32_e32 v228, v224, v50, vcc
	v_cndmask_b32_e32 v229, v225, v51, vcc
	v_cndmask_b32_e32 v230, v48, v222, vcc
	v_cndmask_b32_e32 v231, v49, v223, vcc
	v_cndmask_b32_e32 v232, v50, v224, vcc
	v_cndmask_b32_e32 v233, v51, v225, vcc
	global_store_dwordx4 v236, v[226:229], s[72:73]
	global_store_dwordx4 v237, v[230:233], s[72:73]
	v_mov_b32_dpp v222, v28 row_ror:8 row_mask:0xf bank_mask:0xf
	v_mov_b32_dpp v223, v29 row_ror:8 row_mask:0xf bank_mask:0xf
	v_mov_b32_dpp v224, v30 row_ror:8 row_mask:0xf bank_mask:0xf
	v_mov_b32_dpp v225, v31 row_ror:8 row_mask:0xf bank_mask:0xf
	v_cndmask_b32_e32 v226, v222, v36, vcc
	v_cndmask_b32_e32 v227, v223, v37, vcc
	v_cndmask_b32_e32 v228, v224, v38, vcc
	v_cndmask_b32_e32 v229, v225, v39, vcc
	v_cndmask_b32_e32 v230, v36, v222, vcc
	v_cndmask_b32_e32 v231, v37, v223, vcc
	v_cndmask_b32_e32 v232, v38, v224, vcc
	v_cndmask_b32_e32 v233, v39, v225, vcc
	global_store_dwordx4 v236, v[226:229], s[72:73] offset:512
	global_store_dwordx4 v237, v[230:233], s[72:73] offset:512
	s_waitcnt vmcnt(16)
	v_mov_b32_dpp v222, v128 row_ror:8 row_mask:0xf bank_mask:0xf
	v_mov_b32_dpp v223, v129 row_ror:8 row_mask:0xf bank_mask:0xf
	v_mov_b32_dpp v224, v130 row_ror:8 row_mask:0xf bank_mask:0xf
	v_mov_b32_dpp v225, v131 row_ror:8 row_mask:0xf bank_mask:0xf
	v_mov_b32_dpp v226, v132 row_ror:8 row_mask:0xf bank_mask:0xf
	v_mov_b32_dpp v227, v133 row_ror:8 row_mask:0xf bank_mask:0xf
	v_mov_b32_dpp v228, v134 row_ror:8 row_mask:0xf bank_mask:0xf
	v_mov_b32_dpp v229, v135 row_ror:8 row_mask:0xf bank_mask:0xf
	v_cndmask_b32_e32 v230, v132, v128, vcc
	v_cndmask_b32_e32 v231, v133, v129, vcc
	v_cndmask_b32_e32 v232, v134, v130, vcc
	v_cndmask_b32_e32 v233, v135, v131, vcc
	v_cndmask_b32_e32 v222, v226, v222, vcc
	v_cndmask_b32_e32 v223, v227, v223, vcc
	v_cndmask_b32_e32 v224, v228, v224, vcc
	v_cndmask_b32_e32 v225, v229, v225, vcc
	v_pk_add_f32 v[32:33], v[230:231], v[32:33]
	v_pk_add_f32 v[34:35], v[232:233], v[34:35]
	v_pk_add_f32 v[24:25], v[222:223], v[24:25]
	v_pk_add_f32 v[26:27], v[224:225], v[26:27]
	v_mov_b32_dpp v222, v136 row_ror:8 row_mask:0xf bank_mask:0xf
	v_mov_b32_dpp v223, v137 row_ror:8 row_mask:0xf bank_mask:0xf
	v_mov_b32_dpp v224, v138 row_ror:8 row_mask:0xf bank_mask:0xf
	v_mov_b32_dpp v225, v139 row_ror:8 row_mask:0xf bank_mask:0xf
	v_mov_b32_dpp v226, v140 row_ror:8 row_mask:0xf bank_mask:0xf
	v_mov_b32_dpp v227, v141 row_ror:8 row_mask:0xf bank_mask:0xf
	v_mov_b32_dpp v228, v142 row_ror:8 row_mask:0xf bank_mask:0xf
	v_mov_b32_dpp v229, v143 row_ror:8 row_mask:0xf bank_mask:0xf
	v_cndmask_b32_e32 v230, v140, v136, vcc
	v_cndmask_b32_e32 v231, v141, v137, vcc
	v_cndmask_b32_e32 v232, v142, v138, vcc
	v_cndmask_b32_e32 v233, v143, v139, vcc
	v_cndmask_b32_e32 v222, v226, v222, vcc
	v_cndmask_b32_e32 v223, v227, v223, vcc
	v_cndmask_b32_e32 v224, v228, v224, vcc
	v_cndmask_b32_e32 v225, v229, v225, vcc
	v_pk_add_f32 v[20:21], v[230:231], v[20:21]
	v_pk_add_f32 v[22:23], v[232:233], v[22:23]
	v_pk_add_f32 v[12:13], v[222:223], v[12:13]
	v_pk_add_f32 v[14:15], v[224:225], v[14:15]
	v_add_u32_e32 v236, v192, v234
	v_add_u32_e32 v237, v192, v235
	v_mov_b32_dpp v222, v24 row_ror:8 row_mask:0xf bank_mask:0xf
	v_mov_b32_dpp v223, v25 row_ror:8 row_mask:0xf bank_mask:0xf
	v_mov_b32_dpp v224, v26 row_ror:8 row_mask:0xf bank_mask:0xf
	v_mov_b32_dpp v225, v27 row_ror:8 row_mask:0xf bank_mask:0xf
	v_cndmask_b32_e32 v226, v222, v32, vcc
	v_cndmask_b32_e32 v227, v223, v33, vcc
	v_cndmask_b32_e32 v228, v224, v34, vcc
	v_cndmask_b32_e32 v229, v225, v35, vcc
	v_cndmask_b32_e32 v230, v32, v222, vcc
	v_cndmask_b32_e32 v231, v33, v223, vcc
	v_cndmask_b32_e32 v232, v34, v224, vcc
	v_cndmask_b32_e32 v233, v35, v225, vcc
	global_store_dwordx4 v236, v[226:229], s[72:73]
	global_store_dwordx4 v237, v[230:233], s[72:73]
	v_mov_b32_dpp v222, v12 row_ror:8 row_mask:0xf bank_mask:0xf
	v_mov_b32_dpp v223, v13 row_ror:8 row_mask:0xf bank_mask:0xf
	v_mov_b32_dpp v224, v14 row_ror:8 row_mask:0xf bank_mask:0xf
	v_mov_b32_dpp v225, v15 row_ror:8 row_mask:0xf bank_mask:0xf
	v_cndmask_b32_e32 v226, v222, v20, vcc
	v_cndmask_b32_e32 v227, v223, v21, vcc
	v_cndmask_b32_e32 v228, v224, v22, vcc
	v_cndmask_b32_e32 v229, v225, v23, vcc
	v_cndmask_b32_e32 v230, v20, v222, vcc
	v_cndmask_b32_e32 v231, v21, v223, vcc
	v_cndmask_b32_e32 v232, v22, v224, vcc
	v_cndmask_b32_e32 v233, v23, v225, vcc
	global_store_dwordx4 v236, v[226:229], s[72:73] offset:512
	global_store_dwordx4 v237, v[230:233], s[72:73] offset:512
	s_waitcnt vmcnt(12)
;     __device__ __forceinline__ void operator()(const f32x4 (&acc)[2][2][4][2], const Unit& u, int wr, int wc, int fr, int fq) const {
;     ...
;         for (int gi = 0; gi < 8; ++gi) {
;             const int ai = gi >> 2, m = gi & 3;
;             const int row = row0 + ai * HALF + m * 16;
;             const size_t off = (size_t)row * ldc + col0;
;             if (gi + 1 < 8) {
;                 const size_t offn = (size_t)(row0 + ((gi + 1) >> 2) * HALF + ((gi + 1) & 3) * 16) * ldc + col0;
; #pragma unroll
;                 for (int q = 0; q < 4; ++q) bs[(gi + 1) & 1][q] = *(const f32x4*)(xin + offn + (q >> 1) * HALF + (q & 1) * 16);
;             }
;             float sq = 0.f;
; #pragma unroll
;             for (int q = 0; q < 4; ++q) {
;                 const int bj = q >> 1, n = q & 1;
;                 const f32x4 o = bs[gi & 1][q] + acc[ai][bj][m][n];
;                 *(f32x4*)(out + off + bj * HALF + n * 16) = o;
	v_mov_b32_dpp v222, v144 row_ror:8 row_mask:0xf bank_mask:0xf
	v_mov_b32_dpp v223, v145 row_ror:8 row_mask:0xf bank_mask:0xf
	v_mov_b32_dpp v224, v146 row_ror:8 row_mask:0xf bank_mask:0xf
	v_mov_b32_dpp v225, v147 row_ror:8 row_mask:0xf bank_mask:0xf
	v_mov_b32_dpp v226, v148 row_ror:8 row_mask:0xf bank_mask:0xf
	v_mov_b32_dpp v227, v149 row_ror:8 row_mask:0xf bank_mask:0xf
	v_mov_b32_dpp v228, v150 row_ror:8 row_mask:0xf bank_mask:0xf
	v_mov_b32_dpp v229, v151 row_ror:8 row_mask:0xf bank_mask:0xf
	v_cndmask_b32_e32 v230, v148, v144, vcc
	v_cndmask_b32_e32 v231, v149, v145, vcc
	v_cndmask_b32_e32 v232, v150, v146, vcc
	v_cndmask_b32_e32 v233, v151, v147, vcc
	v_cndmask_b32_e32 v222, v226, v222, vcc
	v_cndmask_b32_e32 v223, v227, v223, vcc
	v_cndmask_b32_e32 v224, v228, v224, vcc
	v_cndmask_b32_e32 v225, v229, v225, vcc
	v_pk_add_f32 v[16:17], v[230:231], v[16:17]
	v_pk_add_f32 v[18:19], v[232:233], v[18:19]
	v_pk_add_f32 v[8:9], v[222:223], v[8:9]
	v_pk_add_f32 v[10:11], v[224:225], v[10:11]
	v_mov_b32_dpp v222, v152 row_ror:8 row_mask:0xf bank_mask:0xf
	v_mov_b32_dpp v223, v153 row_ror:8 row_mask:0xf bank_mask:0xf
	v_mov_b32_dpp v224, v154 row_ror:8 row_mask:0xf bank_mask:0xf
	v_mov_b32_dpp v225, v155 row_ror:8 row_mask:0xf bank_mask:0xf
	v_mov_b32_dpp v226, v156 row_ror:8 row_mask:0xf bank_mask:0xf
	v_mov_b32_dpp v227, v157 row_ror:8 row_mask:0xf bank_mask:0xf
	v_mov_b32_dpp v228, v158 row_ror:8 row_mask:0xf bank_mask:0xf
	v_mov_b32_dpp v229, v159 row_ror:8 row_mask:0xf bank_mask:0xf
	v_cndmask_b32_e32 v230, v156, v152, vcc
	v_cndmask_b32_e32 v231, v157, v153, vcc
	v_cndmask_b32_e32 v232, v158, v154, vcc
	v_cndmask_b32_e32 v233, v159, v155, vcc
	v_cndmask_b32_e32 v222, v226, v222, vcc
	v_cndmask_b32_e32 v223, v227, v223, vcc
	v_cndmask_b32_e32 v224, v228, v224, vcc
	v_cndmask_b32_e32 v225, v229, v225, vcc
	v_pk_add_f32 v[4:5], v[230:231], v[4:5]
	v_pk_add_f32 v[6:7], v[232:233], v[6:7]
	v_pk_add_f32 v[0:1], v[222:223], v[0:1]
	v_pk_add_f32 v[2:3], v[224:225], v[2:3]
	v_add_u32_e32 v236, v193, v234
	v_add_u32_e32 v237, v193, v235
	v_mov_b32_dpp v222, v8 row_ror:8 row_mask:0xf bank_mask:0xf
	v_mov_b32_dpp v223, v9 row_ror:8 row_mask:0xf bank_mask:0xf
	v_mov_b32_dpp v224, v10 row_ror:8 row_mask:0xf bank_mask:0xf
	v_mov_b32_dpp v225, v11 row_ror:8 row_mask:0xf bank_mask:0xf
	v_cndmask_b32_e32 v226, v222, v16, vcc
	v_cndmask_b32_e32 v227, v223, v17, vcc
	v_cndmask_b32_e32 v228, v224, v18, vcc
	v_cndmask_b32_e32 v229, v225, v19, vcc
	v_cndmask_b32_e32 v230, v16, v222, vcc
	v_cndmask_b32_e32 v231, v17, v223, vcc
	v_cndmask_b32_e32 v232, v18, v224, vcc
	v_cndmask_b32_e32 v233, v19, v225, vcc
	global_store_dwordx4 v236, v[226:229], s[72:73]
	global_store_dwordx4 v237, v[230:233], s[72:73]
	v_mov_b32_dpp v222, v0 row_ror:8 row_mask:0xf bank_mask:0xf
	v_mov_b32_dpp v223, v1 row_ror:8 row_mask:0xf bank_mask:0xf
	v_mov_b32_dpp v224, v2 row_ror:8 row_mask:0xf bank_mask:0xf
	v_mov_b32_dpp v225, v3 row_ror:8 row_mask:0xf bank_mask:0xf
	v_cndmask_b32_e32 v226, v222, v4, vcc
	v_cndmask_b32_e32 v227, v223, v5, vcc
	v_cndmask_b32_e32 v228, v224, v6, vcc
	v_cndmask_b32_e32 v229, v225, v7, vcc
	v_cndmask_b32_e32 v230, v4, v222, vcc
	v_cndmask_b32_e32 v231, v5, v223, vcc
	v_cndmask_b32_e32 v232, v6, v224, vcc
	v_cndmask_b32_e32 v233, v7, v225, vcc
	global_store_dwordx4 v236, v[226:229], s[72:73] offset:512
	global_store_dwordx4 v237, v[230:233], s[72:73] offset:512
